# P1 EpiA: 8 row-rstd loads hoisted into peeled K-iteration, epilogue vmcnt(0) dropped
# speedup vs baseline: 1.0061x; 1.0006x over previous
.LBB0_273:
	s_xor_b64 s[34:35], s[6:7], -1
	s_and_b64 s[6:7], s[6:7], exec
	s_cselect_b32 s11, s13, s3
	s_cselect_b32 s15, s12, s2
	s_cselect_b32 s36, s17, s5
	s_cselect_b32 s37, s16, s4
	s_add_u32 s2, s2, 0x40080
	s_addc_u32 s3, s3, 0
	s_add_u32 s38, s4, 0x100
	s_addc_u32 s39, s5, 0
	s_mov_b32 s69, -2
	s_waitcnt lgkmcnt(0)
	ds_read_b128 v[128:131], v211
	ds_read_b128 v[132:135], v211 offset:1024
	ds_read_b128 v[136:139], v211 offset:2048
	ds_read_b128 v[140:143], v211 offset:3072
	s_add_u32 s4, s2, 0xfffc0080
	s_addc_u32 s5, s3, -1
	s_cmp_eq_u32 s69, 12
	s_cselect_b32 s7, s11, s5
	s_cselect_b32 s6, s15, s4
	s_cselect_b32 s5, s36, s39
	s_cselect_b32 s4, s37, s38
	v_lshl_add_u64 v[200:201], s[2:3], 0, v[162:163]
	s_add_i32 m0, s44, 0xc000
	ds_read_b128 v[168:171], v212
	ds_read_b128 v[172:175], v212 offset:1024
	ds_read_b128 v[176:179], v212 offset:2048
	ds_read_b128 v[180:183], v212 offset:3072
	ds_read_b128 v[184:187], v212 offset:4096
	ds_read_b128 v[188:191], v212 offset:5120
	ds_read_b128 v[192:195], v212 offset:6144
	ds_read_b128 v[196:199], v212 offset:7168
	global_load_lds_dwordx4 v[200:201], off
	v_lshl_add_u64 v[200:201], s[2:3], 0, v[164:165]
	s_add_i32 m0, s44, 0xe000
	s_nop 0
	global_load_lds_dwordx4 v[200:201], off
	ds_read_b128 v[222:225], v213
	ds_read_b128 v[226:229], v213 offset:1024
	ds_read_b128 v[230:233], v213 offset:2048
	ds_read_b128 v[234:237], v213 offset:3072
	s_waitcnt lgkmcnt(0)
	s_waitcnt vmcnt(8)
	s_barrier
	s_setprio 1
	v_mfma_f32_16x16x32_bf16 v[124:127], v[128:131], v[168:171], 0
	v_mfma_f32_16x16x32_bf16 v[120:123], v[136:139], v[168:171], 0
	v_mfma_f32_16x16x32_bf16 v[108:111], v[128:131], v[176:179], 0
	v_mfma_f32_16x16x32_bf16 v[104:107], v[136:139], v[176:179], 0
	v_mfma_f32_16x16x32_bf16 v[92:95], v[128:131], v[184:187], 0
	v_mfma_f32_16x16x32_bf16 v[88:91], v[136:139], v[184:187], 0
	v_mfma_f32_16x16x32_bf16 v[76:79], v[128:131], v[192:195], 0
	v_mfma_f32_16x16x32_bf16 v[72:75], v[136:139], v[192:195], 0
	v_mfma_f32_16x16x32_bf16 v[124:127], v[132:135], v[172:175], v[124:127]
	v_mfma_f32_16x16x32_bf16 v[120:123], v[140:143], v[172:175], v[120:123]
	v_mfma_f32_16x16x32_bf16 v[108:111], v[132:135], v[180:183], v[108:111]
	v_mfma_f32_16x16x32_bf16 v[104:107], v[140:143], v[180:183], v[104:107]
	v_mfma_f32_16x16x32_bf16 v[92:95], v[132:135], v[188:191], v[92:95]
	v_mfma_f32_16x16x32_bf16 v[88:91], v[140:143], v[188:191], v[88:91]
	v_mfma_f32_16x16x32_bf16 v[76:79], v[132:135], v[196:199], v[76:79]
	v_mfma_f32_16x16x32_bf16 v[72:75], v[140:143], v[196:199], v[72:75]
	v_mfma_f32_16x16x32_bf16 v[116:119], v[222:225], v[168:171], 0
	v_mfma_f32_16x16x32_bf16 v[112:115], v[230:233], v[168:171], 0
	v_mfma_f32_16x16x32_bf16 v[100:103], v[222:225], v[176:179], 0
	v_mfma_f32_16x16x32_bf16 v[96:99], v[230:233], v[176:179], 0
	v_mfma_f32_16x16x32_bf16 v[84:87], v[222:225], v[184:187], 0
	v_mfma_f32_16x16x32_bf16 v[80:83], v[230:233], v[184:187], 0
	v_mfma_f32_16x16x32_bf16 v[68:71], v[222:225], v[192:195], 0
	v_mfma_f32_16x16x32_bf16 v[64:67], v[230:233], v[192:195], 0
	v_mfma_f32_16x16x32_bf16 v[116:119], v[226:229], v[172:175], v[116:119]
	v_mfma_f32_16x16x32_bf16 v[112:115], v[234:237], v[172:175], v[112:115]
	v_mfma_f32_16x16x32_bf16 v[100:103], v[226:229], v[180:183], v[100:103]
	v_mfma_f32_16x16x32_bf16 v[96:99], v[234:237], v[180:183], v[96:99]
	v_mfma_f32_16x16x32_bf16 v[84:87], v[226:229], v[188:191], v[84:87]
	v_mfma_f32_16x16x32_bf16 v[80:83], v[234:237], v[188:191], v[80:83]
	v_mfma_f32_16x16x32_bf16 v[68:71], v[226:229], v[196:199], v[68:71]
	v_mfma_f32_16x16x32_bf16 v[64:67], v[234:237], v[196:199], v[64:67]
	s_setprio 0
	s_barrier
	s_lshl_b32 s84, s67, 10
	s_cmp_eq_u32 s68, 0
	s_mov_b32 s85, 0x6200000
	s_cselect_b32 s85, s85, 0x6221000
	s_add_u32 s86, s22, s85
	s_addc_u32 s87, s23, 0
	s_add_u32 s86, s86, s84
	s_addc_u32 s87, s87, 0
	v_lshlrev_b32_e32 v221, 2, v204
	v_lshlrev_b32_e32 v247, 2, v205
	v_lshlrev_b32_e32 v250, 2, v206
	v_lshlrev_b32_e32 v251, 2, v207
	v_lshlrev_b32_e32 v252, 2, v204
	v_lshlrev_b32_e32 v253, 2, v204
	v_lshlrev_b32_e32 v254, 2, v204
	v_lshlrev_b32_e32 v255, 2, v204
	global_load_dword v221, v221, s[86:87]
	global_load_dword v247, v247, s[86:87]
	global_load_dword v250, v250, s[86:87]
	global_load_dword v251, v251, s[86:87]
	global_load_dword v252, v252, s[86:87] offset:512
	global_load_dword v253, v253, s[86:87] offset:576
	global_load_dword v254, v254, s[86:87] offset:640
	global_load_dword v255, v255, s[86:87] offset:704
	ds_read_b128 v[168:171], v212 offset:16384
	ds_read_b128 v[172:175], v212 offset:17408
	ds_read_b128 v[176:179], v212 offset:18432
	ds_read_b128 v[180:183], v212 offset:19456
	ds_read_b128 v[184:187], v212 offset:20480
	ds_read_b128 v[188:191], v212 offset:21504
	ds_read_b128 v[192:195], v212 offset:22528
	ds_read_b128 v[196:199], v212 offset:23552
	s_mov_b32 m0, s42
	v_lshl_add_u64 v[200:201], s[4:5], 0, v[144:145]
	global_load_lds_dwordx4 v[200:201], off
	v_lshl_add_u64 v[238:239], s[4:5], 0, v[146:147]
	s_mov_b32 m0, s43
	s_nop 0
	global_load_lds_dwordx4 v[238:239], off
	s_mov_b32 m0, s44
	v_lshl_add_u64 v[240:241], s[6:7], 0, v[144:145]
	global_load_lds_dwordx4 v[240:241], off
	v_lshl_add_u64 v[242:243], s[6:7], 0, v[146:147]
	s_mov_b32 m0, s45
	s_nop 0
	global_load_lds_dwordx4 v[242:243], off
	s_add_u32 s70, s4, 0x40000
	s_addc_u32 s71, s5, 0
	s_mov_b32 m0, s46
	v_lshl_add_u64 v[248:249], s[70:71], 0, v[144:145]
	global_load_lds_dwordx4 v[248:249], off
	v_lshl_add_u64 v[248:249], s[70:71], 0, v[146:147]
	s_mov_b32 m0, s47
	s_nop 0
	global_load_lds_dwordx4 v[248:249], off
	s_waitcnt lgkmcnt(0)
	s_waitcnt vmcnt(16)
	s_barrier
	s_setprio 1
	v_mfma_f32_16x16x32_bf16 v[60:63], v[128:131], v[168:171], 0
	v_mfma_f32_16x16x32_bf16 v[56:59], v[136:139], v[168:171], 0
	v_mfma_f32_16x16x32_bf16 v[44:47], v[128:131], v[176:179], 0
	v_mfma_f32_16x16x32_bf16 v[40:43], v[136:139], v[176:179], 0
	v_mfma_f32_16x16x32_bf16 v[28:31], v[128:131], v[184:187], 0
	v_mfma_f32_16x16x32_bf16 v[24:27], v[136:139], v[184:187], 0
	v_mfma_f32_16x16x32_bf16 v[12:15], v[128:131], v[192:195], 0
	v_mfma_f32_16x16x32_bf16 v[8:11], v[136:139], v[192:195], 0
	v_mfma_f32_16x16x32_bf16 v[60:63], v[132:135], v[172:175], v[60:63]
	v_mfma_f32_16x16x32_bf16 v[56:59], v[140:143], v[172:175], v[56:59]
	v_mfma_f32_16x16x32_bf16 v[44:47], v[132:135], v[180:183], v[44:47]
	v_mfma_f32_16x16x32_bf16 v[40:43], v[140:143], v[180:183], v[40:43]
	v_mfma_f32_16x16x32_bf16 v[28:31], v[132:135], v[188:191], v[28:31]
	v_mfma_f32_16x16x32_bf16 v[24:27], v[140:143], v[188:191], v[24:27]
	v_mfma_f32_16x16x32_bf16 v[12:15], v[132:135], v[196:199], v[12:15]
	v_mfma_f32_16x16x32_bf16 v[8:11], v[140:143], v[196:199], v[8:11]
	v_mfma_f32_16x16x32_bf16 v[52:55], v[222:225], v[168:171], 0
	v_mfma_f32_16x16x32_bf16 v[48:51], v[230:233], v[168:171], 0
	v_mfma_f32_16x16x32_bf16 v[36:39], v[222:225], v[176:179], 0
	v_mfma_f32_16x16x32_bf16 v[32:35], v[230:233], v[176:179], 0
	v_mfma_f32_16x16x32_bf16 v[20:23], v[222:225], v[184:187], 0
	v_mfma_f32_16x16x32_bf16 v[16:19], v[230:233], v[184:187], 0
	v_mfma_f32_16x16x32_bf16 v[4:7], v[222:225], v[192:195], 0
	v_mfma_f32_16x16x32_bf16 v[0:3], v[230:233], v[192:195], 0
	v_mfma_f32_16x16x32_bf16 v[52:55], v[226:229], v[172:175], v[52:55]
	v_mfma_f32_16x16x32_bf16 v[48:51], v[234:237], v[172:175], v[48:51]
	v_mfma_f32_16x16x32_bf16 v[36:39], v[226:229], v[180:183], v[36:39]
	v_mfma_f32_16x16x32_bf16 v[32:35], v[234:237], v[180:183], v[32:35]
	v_mfma_f32_16x16x32_bf16 v[20:23], v[226:229], v[188:191], v[20:23]
	v_mfma_f32_16x16x32_bf16 v[16:19], v[234:237], v[188:191], v[16:19]
	v_mfma_f32_16x16x32_bf16 v[4:7], v[226:229], v[196:199], v[4:7]
	v_mfma_f32_16x16x32_bf16 v[0:3], v[234:237], v[196:199], v[0:3]
	s_setprio 0
	s_barrier
	ds_read_b128 v[128:131], v214
	ds_read_b128 v[132:135], v214 offset:1024
	ds_read_b128 v[136:139], v214 offset:2048
	ds_read_b128 v[140:143], v214 offset:3072
	s_add_u32 s6, s6, 0x40000
	s_addc_u32 s7, s7, 0
	s_mov_b32 m0, s48
	v_lshl_add_u64 v[222:223], s[6:7], 0, v[144:145]
	ds_read_b128 v[168:171], v212 offset:32768
	ds_read_b128 v[172:175], v212 offset:33792
	ds_read_b128 v[176:179], v212 offset:34816
	ds_read_b128 v[180:183], v212 offset:35840
	ds_read_b128 v[184:187], v212 offset:36864
	ds_read_b128 v[188:191], v212 offset:37888
	ds_read_b128 v[192:195], v212 offset:38912
	ds_read_b128 v[196:199], v212 offset:39936
	global_load_lds_dwordx4 v[222:223], off
	v_lshl_add_u64 v[222:223], s[6:7], 0, v[146:147]
	s_mov_b32 m0, s49
	s_nop 0
	global_load_lds_dwordx4 v[222:223], off
	ds_read_b128 v[222:225], v215
	ds_read_b128 v[226:229], v215 offset:1024
	ds_read_b128 v[230:233], v215 offset:2048
	ds_read_b128 v[234:237], v215 offset:3072
	s_waitcnt lgkmcnt(0)
	s_waitcnt vmcnt(16)
	s_barrier
	s_setprio 1
	v_mfma_f32_16x16x32_bf16 v[124:127], v[128:131], v[168:171], v[124:127]
	v_mfma_f32_16x16x32_bf16 v[120:123], v[136:139], v[168:171], v[120:123]
	v_mfma_f32_16x16x32_bf16 v[108:111], v[128:131], v[176:179], v[108:111]
	v_mfma_f32_16x16x32_bf16 v[104:107], v[136:139], v[176:179], v[104:107]
	v_mfma_f32_16x16x32_bf16 v[92:95], v[128:131], v[184:187], v[92:95]
	v_mfma_f32_16x16x32_bf16 v[88:91], v[136:139], v[184:187], v[88:91]
	v_mfma_f32_16x16x32_bf16 v[76:79], v[128:131], v[192:195], v[76:79]
	v_mfma_f32_16x16x32_bf16 v[72:75], v[136:139], v[192:195], v[72:75]
	v_mfma_f32_16x16x32_bf16 v[124:127], v[132:135], v[172:175], v[124:127]
	v_mfma_f32_16x16x32_bf16 v[120:123], v[140:143], v[172:175], v[120:123]
	v_mfma_f32_16x16x32_bf16 v[108:111], v[132:135], v[180:183], v[108:111]
	v_mfma_f32_16x16x32_bf16 v[104:107], v[140:143], v[180:183], v[104:107]
	v_mfma_f32_16x16x32_bf16 v[92:95], v[132:135], v[188:191], v[92:95]
	v_mfma_f32_16x16x32_bf16 v[88:91], v[140:143], v[188:191], v[88:91]
	v_mfma_f32_16x16x32_bf16 v[76:79], v[132:135], v[196:199], v[76:79]
	v_mfma_f32_16x16x32_bf16 v[72:75], v[140:143], v[196:199], v[72:75]
	v_mfma_f32_16x16x32_bf16 v[116:119], v[222:225], v[168:171], v[116:119]
	v_mfma_f32_16x16x32_bf16 v[112:115], v[230:233], v[168:171], v[112:115]
	v_mfma_f32_16x16x32_bf16 v[100:103], v[222:225], v[176:179], v[100:103]
	v_mfma_f32_16x16x32_bf16 v[96:99], v[230:233], v[176:179], v[96:99]
	v_mfma_f32_16x16x32_bf16 v[84:87], v[222:225], v[184:187], v[84:87]
	v_mfma_f32_16x16x32_bf16 v[80:83], v[230:233], v[184:187], v[80:83]
	v_mfma_f32_16x16x32_bf16 v[68:71], v[222:225], v[192:195], v[68:71]
	v_mfma_f32_16x16x32_bf16 v[64:67], v[230:233], v[192:195], v[64:67]
	v_mfma_f32_16x16x32_bf16 v[116:119], v[226:229], v[172:175], v[116:119]
	v_mfma_f32_16x16x32_bf16 v[112:115], v[234:237], v[172:175], v[112:115]
	v_mfma_f32_16x16x32_bf16 v[100:103], v[226:229], v[180:183], v[100:103]
	v_mfma_f32_16x16x32_bf16 v[96:99], v[234:237], v[180:183], v[96:99]
	v_mfma_f32_16x16x32_bf16 v[84:87], v[226:229], v[188:191], v[84:87]
	v_mfma_f32_16x16x32_bf16 v[80:83], v[234:237], v[188:191], v[80:83]
	v_mfma_f32_16x16x32_bf16 v[68:71], v[226:229], v[196:199], v[68:71]
	v_mfma_f32_16x16x32_bf16 v[64:67], v[234:237], v[196:199], v[64:67]
	s_setprio 0
	s_barrier
	ds_read_b128 v[168:171], v212 offset:49152
	ds_read_b128 v[172:175], v212 offset:50176
	ds_read_b128 v[176:179], v212 offset:51200
	ds_read_b128 v[180:183], v212 offset:52224
	ds_read_b128 v[184:187], v212 offset:53248
	ds_read_b128 v[188:191], v212 offset:54272
	ds_read_b128 v[192:195], v212 offset:55296
	ds_read_b128 v[196:199], v212 offset:56320
	s_mov_b32 m0, s51
	v_lshl_add_u64 v[200:201], v[200:201], 0, s[18:19]
	global_load_lds_dwordx4 v[200:201], off
	v_lshl_add_u64 v[200:201], v[238:239], 0, s[18:19]
	s_mov_b32 m0, s52
	s_nop 0
	global_load_lds_dwordx4 v[200:201], off
	s_mov_b32 m0, s54
	v_lshl_add_u64 v[200:201], v[240:241], 0, s[18:19]
	global_load_lds_dwordx4 v[200:201], off
	v_lshl_add_u64 v[200:201], v[242:243], 0, s[18:19]
	s_mov_b32 m0, s55
	s_nop 0
	global_load_lds_dwordx4 v[200:201], off
	s_add_u32 s4, s4, 0x40080
	s_addc_u32 s5, s5, 0
	s_mov_b32 m0, s56
	v_lshl_add_u64 v[248:249], s[4:5], 0, v[144:145]
	global_load_lds_dwordx4 v[248:249], off
	v_lshl_add_u64 v[248:249], s[4:5], 0, v[146:147]
	s_mov_b32 m0, s57
	s_nop 0
	global_load_lds_dwordx4 v[248:249], off
	s_waitcnt lgkmcnt(0)
	s_waitcnt vmcnt(8)
	s_barrier
	s_setprio 1
	v_mfma_f32_16x16x32_bf16 v[60:63], v[128:131], v[168:171], v[60:63]
	v_mfma_f32_16x16x32_bf16 v[56:59], v[136:139], v[168:171], v[56:59]
	v_mfma_f32_16x16x32_bf16 v[44:47], v[128:131], v[176:179], v[44:47]
	v_mfma_f32_16x16x32_bf16 v[40:43], v[136:139], v[176:179], v[40:43]
	v_mfma_f32_16x16x32_bf16 v[28:31], v[128:131], v[184:187], v[28:31]
	v_mfma_f32_16x16x32_bf16 v[24:27], v[136:139], v[184:187], v[24:27]
	v_mfma_f32_16x16x32_bf16 v[12:15], v[128:131], v[192:195], v[12:15]
	v_mfma_f32_16x16x32_bf16 v[8:11], v[136:139], v[192:195], v[8:11]
	v_mfma_f32_16x16x32_bf16 v[60:63], v[132:135], v[172:175], v[60:63]
	v_mfma_f32_16x16x32_bf16 v[56:59], v[140:143], v[172:175], v[56:59]
	v_mfma_f32_16x16x32_bf16 v[44:47], v[132:135], v[180:183], v[44:47]
	v_mfma_f32_16x16x32_bf16 v[40:43], v[140:143], v[180:183], v[40:43]
	v_mfma_f32_16x16x32_bf16 v[28:31], v[132:135], v[188:191], v[28:31]
	v_mfma_f32_16x16x32_bf16 v[24:27], v[140:143], v[188:191], v[24:27]
	v_mfma_f32_16x16x32_bf16 v[12:15], v[132:135], v[196:199], v[12:15]
	v_mfma_f32_16x16x32_bf16 v[8:11], v[140:143], v[196:199], v[8:11]
	v_mfma_f32_16x16x32_bf16 v[52:55], v[222:225], v[168:171], v[52:55]
	v_mfma_f32_16x16x32_bf16 v[48:51], v[230:233], v[168:171], v[48:51]
	v_mfma_f32_16x16x32_bf16 v[36:39], v[222:225], v[176:179], v[36:39]
	v_mfma_f32_16x16x32_bf16 v[32:35], v[230:233], v[176:179], v[32:35]
	v_mfma_f32_16x16x32_bf16 v[20:23], v[222:225], v[184:187], v[20:23]
	v_mfma_f32_16x16x32_bf16 v[16:19], v[230:233], v[184:187], v[16:19]
	v_mfma_f32_16x16x32_bf16 v[4:7], v[222:225], v[192:195], v[4:7]
	v_mfma_f32_16x16x32_bf16 v[0:3], v[230:233], v[192:195], v[0:3]
	v_mfma_f32_16x16x32_bf16 v[52:55], v[226:229], v[172:175], v[52:55]
	v_mfma_f32_16x16x32_bf16 v[48:51], v[234:237], v[172:175], v[48:51]
	v_mfma_f32_16x16x32_bf16 v[36:39], v[226:229], v[180:183], v[36:39]
	v_mfma_f32_16x16x32_bf16 v[32:35], v[234:237], v[180:183], v[32:35]
	v_mfma_f32_16x16x32_bf16 v[20:23], v[226:229], v[188:191], v[20:23]
	v_mfma_f32_16x16x32_bf16 v[16:19], v[234:237], v[188:191], v[16:19]
	v_mfma_f32_16x16x32_bf16 v[4:7], v[226:229], v[196:199], v[4:7]
	v_mfma_f32_16x16x32_bf16 v[0:3], v[234:237], v[196:199], v[0:3]
	s_setprio 0
	s_add_i32 s69, s69, 2
	s_add_u32 s2, s2, 0x100
	s_addc_u32 s3, s3, 0
	s_add_u32 s38, s38, 0x100
	s_addc_u32 s39, s39, 0
	s_cmp_gt_u32 s69, 13
	s_barrier
.LBB0_274:
	ds_read_b128 v[128:131], v211
	ds_read_b128 v[132:135], v211 offset:1024
	ds_read_b128 v[136:139], v211 offset:2048
	ds_read_b128 v[140:143], v211 offset:3072
	s_add_u32 s4, s2, 0xfffc0080
	s_addc_u32 s5, s3, -1
	s_cmp_eq_u32 s69, 12
	s_cselect_b32 s7, s11, s5
	s_cselect_b32 s6, s15, s4
	s_cselect_b32 s5, s36, s39
	s_cselect_b32 s4, s37, s38
	v_lshl_add_u64 v[200:201], s[2:3], 0, v[162:163]
	s_add_i32 m0, s44, 0xc000
	ds_read_b128 v[168:171], v212
	ds_read_b128 v[172:175], v212 offset:1024
	ds_read_b128 v[176:179], v212 offset:2048
	ds_read_b128 v[180:183], v212 offset:3072
	ds_read_b128 v[184:187], v212 offset:4096
	ds_read_b128 v[188:191], v212 offset:5120
	ds_read_b128 v[192:195], v212 offset:6144
	ds_read_b128 v[196:199], v212 offset:7168
	global_load_lds_dwordx4 v[200:201], off
	v_lshl_add_u64 v[200:201], s[2:3], 0, v[164:165]
	s_add_i32 m0, s44, 0xe000
	s_nop 0
	global_load_lds_dwordx4 v[200:201], off
	ds_read_b128 v[222:225], v213
	ds_read_b128 v[226:229], v213 offset:1024
	ds_read_b128 v[230:233], v213 offset:2048
	ds_read_b128 v[234:237], v213 offset:3072
	s_waitcnt lgkmcnt(0)
	s_waitcnt vmcnt(8)
	s_barrier
	s_setprio 1
	v_mfma_f32_16x16x32_bf16 v[124:127], v[128:131], v[168:171], v[124:127]
	v_mfma_f32_16x16x32_bf16 v[120:123], v[136:139], v[168:171], v[120:123]
	v_mfma_f32_16x16x32_bf16 v[108:111], v[128:131], v[176:179], v[108:111]
	v_mfma_f32_16x16x32_bf16 v[104:107], v[136:139], v[176:179], v[104:107]
	v_mfma_f32_16x16x32_bf16 v[92:95], v[128:131], v[184:187], v[92:95]
	v_mfma_f32_16x16x32_bf16 v[88:91], v[136:139], v[184:187], v[88:91]
	v_mfma_f32_16x16x32_bf16 v[76:79], v[128:131], v[192:195], v[76:79]
	v_mfma_f32_16x16x32_bf16 v[72:75], v[136:139], v[192:195], v[72:75]
	v_mfma_f32_16x16x32_bf16 v[124:127], v[132:135], v[172:175], v[124:127]
	v_mfma_f32_16x16x32_bf16 v[120:123], v[140:143], v[172:175], v[120:123]
	v_mfma_f32_16x16x32_bf16 v[108:111], v[132:135], v[180:183], v[108:111]
	v_mfma_f32_16x16x32_bf16 v[104:107], v[140:143], v[180:183], v[104:107]
	v_mfma_f32_16x16x32_bf16 v[92:95], v[132:135], v[188:191], v[92:95]
	v_mfma_f32_16x16x32_bf16 v[88:91], v[140:143], v[188:191], v[88:91]
	v_mfma_f32_16x16x32_bf16 v[76:79], v[132:135], v[196:199], v[76:79]
	v_mfma_f32_16x16x32_bf16 v[72:75], v[140:143], v[196:199], v[72:75]
	v_mfma_f32_16x16x32_bf16 v[116:119], v[222:225], v[168:171], v[116:119]
	v_mfma_f32_16x16x32_bf16 v[112:115], v[230:233], v[168:171], v[112:115]
	v_mfma_f32_16x16x32_bf16 v[100:103], v[222:225], v[176:179], v[100:103]
	v_mfma_f32_16x16x32_bf16 v[96:99], v[230:233], v[176:179], v[96:99]
	v_mfma_f32_16x16x32_bf16 v[84:87], v[222:225], v[184:187], v[84:87]
	v_mfma_f32_16x16x32_bf16 v[80:83], v[230:233], v[184:187], v[80:83]
	v_mfma_f32_16x16x32_bf16 v[68:71], v[222:225], v[192:195], v[68:71]
	v_mfma_f32_16x16x32_bf16 v[64:67], v[230:233], v[192:195], v[64:67]
	v_mfma_f32_16x16x32_bf16 v[116:119], v[226:229], v[172:175], v[116:119]
	v_mfma_f32_16x16x32_bf16 v[112:115], v[234:237], v[172:175], v[112:115]
	v_mfma_f32_16x16x32_bf16 v[100:103], v[226:229], v[180:183], v[100:103]
	v_mfma_f32_16x16x32_bf16 v[96:99], v[234:237], v[180:183], v[96:99]
	v_mfma_f32_16x16x32_bf16 v[84:87], v[226:229], v[188:191], v[84:87]
	v_mfma_f32_16x16x32_bf16 v[80:83], v[234:237], v[188:191], v[80:83]
	v_mfma_f32_16x16x32_bf16 v[68:71], v[226:229], v[196:199], v[68:71]
	v_mfma_f32_16x16x32_bf16 v[64:67], v[234:237], v[196:199], v[64:67]
	s_setprio 0
	s_barrier
	ds_read_b128 v[168:171], v212 offset:16384
	ds_read_b128 v[172:175], v212 offset:17408
	ds_read_b128 v[176:179], v212 offset:18432
	ds_read_b128 v[180:183], v212 offset:19456
	ds_read_b128 v[184:187], v212 offset:20480
	ds_read_b128 v[188:191], v212 offset:21504
	ds_read_b128 v[192:195], v212 offset:22528
	ds_read_b128 v[196:199], v212 offset:23552
	s_mov_b32 m0, s42
	v_lshl_add_u64 v[200:201], s[4:5], 0, v[144:145]
	global_load_lds_dwordx4 v[200:201], off
	v_lshl_add_u64 v[238:239], s[4:5], 0, v[146:147]
	s_mov_b32 m0, s43
	s_nop 0
	global_load_lds_dwordx4 v[238:239], off
	s_mov_b32 m0, s44
	v_lshl_add_u64 v[240:241], s[6:7], 0, v[144:145]
	global_load_lds_dwordx4 v[240:241], off
	v_lshl_add_u64 v[242:243], s[6:7], 0, v[146:147]
	s_mov_b32 m0, s45
	s_nop 0
	global_load_lds_dwordx4 v[242:243], off
	s_add_u32 s70, s4, 0x40000
	s_addc_u32 s71, s5, 0
	s_mov_b32 m0, s46
	v_lshl_add_u64 v[248:249], s[70:71], 0, v[144:145]
	global_load_lds_dwordx4 v[248:249], off
	v_lshl_add_u64 v[248:249], s[70:71], 0, v[146:147]
	s_mov_b32 m0, s47
	s_nop 0
	global_load_lds_dwordx4 v[248:249], off
	s_waitcnt lgkmcnt(0)
	s_waitcnt vmcnt(8)
	s_barrier
	s_setprio 1
	v_mfma_f32_16x16x32_bf16 v[60:63], v[128:131], v[168:171], v[60:63]
	v_mfma_f32_16x16x32_bf16 v[56:59], v[136:139], v[168:171], v[56:59]
	v_mfma_f32_16x16x32_bf16 v[44:47], v[128:131], v[176:179], v[44:47]
	v_mfma_f32_16x16x32_bf16 v[40:43], v[136:139], v[176:179], v[40:43]
	v_mfma_f32_16x16x32_bf16 v[28:31], v[128:131], v[184:187], v[28:31]
	v_mfma_f32_16x16x32_bf16 v[24:27], v[136:139], v[184:187], v[24:27]
	v_mfma_f32_16x16x32_bf16 v[12:15], v[128:131], v[192:195], v[12:15]
	v_mfma_f32_16x16x32_bf16 v[8:11], v[136:139], v[192:195], v[8:11]
	v_mfma_f32_16x16x32_bf16 v[60:63], v[132:135], v[172:175], v[60:63]
	v_mfma_f32_16x16x32_bf16 v[56:59], v[140:143], v[172:175], v[56:59]
	v_mfma_f32_16x16x32_bf16 v[44:47], v[132:135], v[180:183], v[44:47]
	v_mfma_f32_16x16x32_bf16 v[40:43], v[140:143], v[180:183], v[40:43]
	v_mfma_f32_16x16x32_bf16 v[28:31], v[132:135], v[188:191], v[28:31]
	v_mfma_f32_16x16x32_bf16 v[24:27], v[140:143], v[188:191], v[24:27]
	v_mfma_f32_16x16x32_bf16 v[12:15], v[132:135], v[196:199], v[12:15]
	v_mfma_f32_16x16x32_bf16 v[8:11], v[140:143], v[196:199], v[8:11]
	v_mfma_f32_16x16x32_bf16 v[52:55], v[222:225], v[168:171], v[52:55]
	v_mfma_f32_16x16x32_bf16 v[48:51], v[230:233], v[168:171], v[48:51]
	v_mfma_f32_16x16x32_bf16 v[36:39], v[222:225], v[176:179], v[36:39]
	v_mfma_f32_16x16x32_bf16 v[32:35], v[230:233], v[176:179], v[32:35]
	v_mfma_f32_16x16x32_bf16 v[20:23], v[222:225], v[184:187], v[20:23]
	v_mfma_f32_16x16x32_bf16 v[16:19], v[230:233], v[184:187], v[16:19]
	v_mfma_f32_16x16x32_bf16 v[4:7], v[222:225], v[192:195], v[4:7]
	v_mfma_f32_16x16x32_bf16 v[0:3], v[230:233], v[192:195], v[0:3]
	v_mfma_f32_16x16x32_bf16 v[52:55], v[226:229], v[172:175], v[52:55]
	v_mfma_f32_16x16x32_bf16 v[48:51], v[234:237], v[172:175], v[48:51]
	v_mfma_f32_16x16x32_bf16 v[36:39], v[226:229], v[180:183], v[36:39]
	v_mfma_f32_16x16x32_bf16 v[32:35], v[234:237], v[180:183], v[32:35]
	v_mfma_f32_16x16x32_bf16 v[20:23], v[226:229], v[188:191], v[20:23]
	v_mfma_f32_16x16x32_bf16 v[16:19], v[234:237], v[188:191], v[16:19]
	v_mfma_f32_16x16x32_bf16 v[4:7], v[226:229], v[196:199], v[4:7]
	v_mfma_f32_16x16x32_bf16 v[0:3], v[234:237], v[196:199], v[0:3]
	s_setprio 0
	s_barrier
	ds_read_b128 v[128:131], v214
	ds_read_b128 v[132:135], v214 offset:1024
	ds_read_b128 v[136:139], v214 offset:2048
	ds_read_b128 v[140:143], v214 offset:3072
	s_add_u32 s6, s6, 0x40000
	s_addc_u32 s7, s7, 0
	s_mov_b32 m0, s48
	v_lshl_add_u64 v[222:223], s[6:7], 0, v[144:145]
	ds_read_b128 v[168:171], v212 offset:32768
	ds_read_b128 v[172:175], v212 offset:33792
	ds_read_b128 v[176:179], v212 offset:34816
	ds_read_b128 v[180:183], v212 offset:35840
	ds_read_b128 v[184:187], v212 offset:36864
	ds_read_b128 v[188:191], v212 offset:37888
	ds_read_b128 v[192:195], v212 offset:38912
	ds_read_b128 v[196:199], v212 offset:39936
	global_load_lds_dwordx4 v[222:223], off
	v_lshl_add_u64 v[222:223], s[6:7], 0, v[146:147]
	s_mov_b32 m0, s49
	s_nop 0
	global_load_lds_dwordx4 v[222:223], off
	ds_read_b128 v[222:225], v215
	ds_read_b128 v[226:229], v215 offset:1024
	ds_read_b128 v[230:233], v215 offset:2048
	ds_read_b128 v[234:237], v215 offset:3072
	s_waitcnt lgkmcnt(0)
	s_waitcnt vmcnt(8)
	s_barrier
	s_setprio 1
	v_mfma_f32_16x16x32_bf16 v[124:127], v[128:131], v[168:171], v[124:127]
	v_mfma_f32_16x16x32_bf16 v[120:123], v[136:139], v[168:171], v[120:123]
	v_mfma_f32_16x16x32_bf16 v[108:111], v[128:131], v[176:179], v[108:111]
	v_mfma_f32_16x16x32_bf16 v[104:107], v[136:139], v[176:179], v[104:107]
	v_mfma_f32_16x16x32_bf16 v[92:95], v[128:131], v[184:187], v[92:95]
	v_mfma_f32_16x16x32_bf16 v[88:91], v[136:139], v[184:187], v[88:91]
	v_mfma_f32_16x16x32_bf16 v[76:79], v[128:131], v[192:195], v[76:79]
	v_mfma_f32_16x16x32_bf16 v[72:75], v[136:139], v[192:195], v[72:75]
	v_mfma_f32_16x16x32_bf16 v[124:127], v[132:135], v[172:175], v[124:127]
	v_mfma_f32_16x16x32_bf16 v[120:123], v[140:143], v[172:175], v[120:123]
	v_mfma_f32_16x16x32_bf16 v[108:111], v[132:135], v[180:183], v[108:111]
	v_mfma_f32_16x16x32_bf16 v[104:107], v[140:143], v[180:183], v[104:107]
	v_mfma_f32_16x16x32_bf16 v[92:95], v[132:135], v[188:191], v[92:95]
	v_mfma_f32_16x16x32_bf16 v[88:91], v[140:143], v[188:191], v[88:91]
	v_mfma_f32_16x16x32_bf16 v[76:79], v[132:135], v[196:199], v[76:79]
	v_mfma_f32_16x16x32_bf16 v[72:75], v[140:143], v[196:199], v[72:75]
	v_mfma_f32_16x16x32_bf16 v[116:119], v[222:225], v[168:171], v[116:119]
	v_mfma_f32_16x16x32_bf16 v[112:115], v[230:233], v[168:171], v[112:115]
	v_mfma_f32_16x16x32_bf16 v[100:103], v[222:225], v[176:179], v[100:103]
	v_mfma_f32_16x16x32_bf16 v[96:99], v[230:233], v[176:179], v[96:99]
	v_mfma_f32_16x16x32_bf16 v[84:87], v[222:225], v[184:187], v[84:87]
	v_mfma_f32_16x16x32_bf16 v[80:83], v[230:233], v[184:187], v[80:83]
	v_mfma_f32_16x16x32_bf16 v[68:71], v[222:225], v[192:195], v[68:71]
	v_mfma_f32_16x16x32_bf16 v[64:67], v[230:233], v[192:195], v[64:67]
	v_mfma_f32_16x16x32_bf16 v[116:119], v[226:229], v[172:175], v[116:119]
	v_mfma_f32_16x16x32_bf16 v[112:115], v[234:237], v[172:175], v[112:115]
	v_mfma_f32_16x16x32_bf16 v[100:103], v[226:229], v[180:183], v[100:103]
	v_mfma_f32_16x16x32_bf16 v[96:99], v[234:237], v[180:183], v[96:99]
	v_mfma_f32_16x16x32_bf16 v[84:87], v[226:229], v[188:191], v[84:87]
	v_mfma_f32_16x16x32_bf16 v[80:83], v[234:237], v[188:191], v[80:83]
	v_mfma_f32_16x16x32_bf16 v[68:71], v[226:229], v[196:199], v[68:71]
	v_mfma_f32_16x16x32_bf16 v[64:67], v[234:237], v[196:199], v[64:67]
	s_setprio 0
	s_barrier
	ds_read_b128 v[168:171], v212 offset:49152
	ds_read_b128 v[172:175], v212 offset:50176
	ds_read_b128 v[176:179], v212 offset:51200
	ds_read_b128 v[180:183], v212 offset:52224
	ds_read_b128 v[184:187], v212 offset:53248
	ds_read_b128 v[188:191], v212 offset:54272
	ds_read_b128 v[192:195], v212 offset:55296
	ds_read_b128 v[196:199], v212 offset:56320
	s_mov_b32 m0, s51
	v_lshl_add_u64 v[200:201], v[200:201], 0, s[18:19]
	global_load_lds_dwordx4 v[200:201], off
	v_lshl_add_u64 v[200:201], v[238:239], 0, s[18:19]
	s_mov_b32 m0, s52
	s_nop 0
	global_load_lds_dwordx4 v[200:201], off
	s_mov_b32 m0, s54
	v_lshl_add_u64 v[200:201], v[240:241], 0, s[18:19]
	global_load_lds_dwordx4 v[200:201], off
	v_lshl_add_u64 v[200:201], v[242:243], 0, s[18:19]
	s_mov_b32 m0, s55
	s_nop 0
	global_load_lds_dwordx4 v[200:201], off
	s_add_u32 s4, s4, 0x40080
	s_addc_u32 s5, s5, 0
	s_mov_b32 m0, s56
	v_lshl_add_u64 v[248:249], s[4:5], 0, v[144:145]
	global_load_lds_dwordx4 v[248:249], off
	v_lshl_add_u64 v[248:249], s[4:5], 0, v[146:147]
	s_mov_b32 m0, s57
	s_nop 0
	global_load_lds_dwordx4 v[248:249], off
	s_waitcnt lgkmcnt(0)
	s_waitcnt vmcnt(8)
	s_barrier
	s_setprio 1
	v_mfma_f32_16x16x32_bf16 v[60:63], v[128:131], v[168:171], v[60:63]
	v_mfma_f32_16x16x32_bf16 v[56:59], v[136:139], v[168:171], v[56:59]
	v_mfma_f32_16x16x32_bf16 v[44:47], v[128:131], v[176:179], v[44:47]
	v_mfma_f32_16x16x32_bf16 v[40:43], v[136:139], v[176:179], v[40:43]
	v_mfma_f32_16x16x32_bf16 v[28:31], v[128:131], v[184:187], v[28:31]
	v_mfma_f32_16x16x32_bf16 v[24:27], v[136:139], v[184:187], v[24:27]
	v_mfma_f32_16x16x32_bf16 v[12:15], v[128:131], v[192:195], v[12:15]
	v_mfma_f32_16x16x32_bf16 v[8:11], v[136:139], v[192:195], v[8:11]
	v_mfma_f32_16x16x32_bf16 v[60:63], v[132:135], v[172:175], v[60:63]
	v_mfma_f32_16x16x32_bf16 v[56:59], v[140:143], v[172:175], v[56:59]
	v_mfma_f32_16x16x32_bf16 v[44:47], v[132:135], v[180:183], v[44:47]
	v_mfma_f32_16x16x32_bf16 v[40:43], v[140:143], v[180:183], v[40:43]
	v_mfma_f32_16x16x32_bf16 v[28:31], v[132:135], v[188:191], v[28:31]
	v_mfma_f32_16x16x32_bf16 v[24:27], v[140:143], v[188:191], v[24:27]
	v_mfma_f32_16x16x32_bf16 v[12:15], v[132:135], v[196:199], v[12:15]
	v_mfma_f32_16x16x32_bf16 v[8:11], v[140:143], v[196:199], v[8:11]
	v_mfma_f32_16x16x32_bf16 v[52:55], v[222:225], v[168:171], v[52:55]
	v_mfma_f32_16x16x32_bf16 v[48:51], v[230:233], v[168:171], v[48:51]
	v_mfma_f32_16x16x32_bf16 v[36:39], v[222:225], v[176:179], v[36:39]
	v_mfma_f32_16x16x32_bf16 v[32:35], v[230:233], v[176:179], v[32:35]
	v_mfma_f32_16x16x32_bf16 v[20:23], v[222:225], v[184:187], v[20:23]
	v_mfma_f32_16x16x32_bf16 v[16:19], v[230:233], v[184:187], v[16:19]
	v_mfma_f32_16x16x32_bf16 v[4:7], v[222:225], v[192:195], v[4:7]
	v_mfma_f32_16x16x32_bf16 v[0:3], v[230:233], v[192:195], v[0:3]
	v_mfma_f32_16x16x32_bf16 v[52:55], v[226:229], v[172:175], v[52:55]
	v_mfma_f32_16x16x32_bf16 v[48:51], v[234:237], v[172:175], v[48:51]
	v_mfma_f32_16x16x32_bf16 v[36:39], v[226:229], v[180:183], v[36:39]
	v_mfma_f32_16x16x32_bf16 v[32:35], v[234:237], v[180:183], v[32:35]
	v_mfma_f32_16x16x32_bf16 v[20:23], v[226:229], v[188:191], v[20:23]
	v_mfma_f32_16x16x32_bf16 v[16:19], v[234:237], v[188:191], v[16:19]
	v_mfma_f32_16x16x32_bf16 v[4:7], v[226:229], v[196:199], v[4:7]
	v_mfma_f32_16x16x32_bf16 v[0:3], v[234:237], v[196:199], v[0:3]
	s_setprio 0
	s_add_i32 s69, s69, 2
	s_add_u32 s2, s2, 0x100
	s_addc_u32 s3, s3, 0
	s_add_u32 s38, s38, 0x100
	s_addc_u32 s39, s39, 0
	s_cmp_gt_u32 s69, 13
	s_barrier
	s_cbranch_scc0 .LBB0_274
	s_lshl_b32 s11, s67, 8
	s_cmp_eq_u32 s68, 0
	s_mov_b32 s2, 0x6200000
	s_cselect_b32 s2, s2, 0x6221000
	s_add_u32 s2, s22, s2
	v_add_u32_e32 v176, s11, v204
	s_addc_u32 s3, s23, 0
	v_ashrrev_i32_e32 v177, 31, v176
	v_add_u32_e32 v198, s11, v205
	v_add_u32_e32 v196, s11, v206
	v_add_u32_e32 v194, s11, v207
	v_add_u32_e32 v192, 0x80, v176
	v_add_u32_e32 v190, 0x90, v176
	v_add_u32_e32 v188, 0xa0, v176
	v_add_u32_e32 v186, 0xb0, v176
	v_ashrrev_i32_e32 v199, 31, v198
	v_ashrrev_i32_e32 v197, 31, v196
	v_ashrrev_i32_e32 v195, 31, v194
	v_ashrrev_i32_e32 v193, 31, v192
	v_ashrrev_i32_e32 v191, 31, v190
	v_ashrrev_i32_e32 v189, 31, v188
	v_ashrrev_i32_e32 v187, 31, v186
	v_mov_b32_e32 v184, v221
	v_mov_b32_e32 v182, v247
	v_mov_b32_e32 v180, v250
	v_mov_b32_e32 v178, v251
	v_mov_b32_e32 v174, v252
	v_mov_b32_e32 v172, v253
	v_mov_b32_e32 v170, v254
	v_mov_b32_e32 v168, v255
	s_cmp_lt_i32 s33, 2
	s_cselect_b64 s[38:39], -1, 0
	s_cmp_gt_i32 s33, 1
	s_cselect_b64 s[2:3], -1, 0
	v_cndmask_b32_e64 v128, 0, 1, s[2:3]
	s_cmp_lg_u32 s68, 0
	s_mov_b64 s[6:7], -1
	v_cmp_ne_u32_e64 s[4:5], 1, v128
	s_cbranch_scc0 .LBB0_293
	s_lshl_b32 s6, s33, 8
	s_and_b32 s6, s6, 0x100
	v_or_b32_e32 v169, s6, v210
	s_and_b64 s[6:7], s[38:39], exec
	s_mov_b32 s6, 0x8600000
	s_cselect_b32 s6, s6, 0x8a00000
	s_add_u32 s6, s20, s6
	v_lshlrev_b32_e32 v148, 1, v169
	s_addc_u32 s7, s21, 0
	v_lshlrev_b64 v[222:223], 11, v[176:177]
	v_lshl_add_u64 v[200:201], s[26:27], 0, v[148:149]
	v_lshl_add_u64 v[222:223], s[6:7], 0, v[222:223]
	v_lshlrev_b32_e32 v148, 2, v169
	v_pk_mul_f32 v[130:131], v[126:127], v[184:185] op_sel_hi:[1,0]
	v_pk_mul_f32 v[128:129], v[124:125], v[184:185] op_sel_hi:[1,0]
	v_pk_mul_f32 v[134:135], v[122:123], v[184:185] op_sel_hi:[1,0]
	v_pk_mul_f32 v[132:133], v[120:121], v[184:185] op_sel_hi:[1,0]
	v_pk_mul_f32 v[138:139], v[118:119], v[184:185] op_sel_hi:[1,0]
	v_pk_mul_f32 v[136:137], v[116:117], v[184:185] op_sel_hi:[1,0]
	v_pk_mul_f32 v[142:143], v[114:115], v[184:185] op_sel_hi:[1,0]
	v_pk_mul_f32 v[140:141], v[112:113], v[184:185] op_sel_hi:[1,0]
	v_lshl_add_u64 v[222:223], v[222:223], 0, v[148:149]
	s_and_b64 vcc, exec, s[4:5]
	global_store_dwordx4 v[222:223], v[128:131], off
	global_store_dwordx4 v[222:223], v[132:135], off offset:16
	global_store_dwordx4 v[222:223], v[136:139], off offset:128
	global_store_dwordx4 v[222:223], v[140:143], off offset:144
	s_cbranch_vccnz .LBB0_278
	v_lshlrev_b64 v[222:223], 9, v[176:177]
	v_lshl_add_u64 v[222:223], v[222:223], 1, v[200:201]
	v_cvt_pk_bf16_f32 v128, v128, v129
	v_cvt_pk_bf16_f32 v129, v130, v131
	v_cvt_pk_bf16_f32 v130, v132, v133
	v_cvt_pk_bf16_f32 v131, v134, v135
	global_store_dwordx4 v[222:223], v[128:131], off nt
	s_nop 1
	v_cvt_pk_bf16_f32 v128, v136, v137
	v_cvt_pk_bf16_f32 v129, v138, v139
	v_cvt_pk_bf16_f32 v130, v140, v141
	v_cvt_pk_bf16_f32 v131, v142, v143
	global_store_dwordx4 v[222:223], v[128:131], off offset:64 nt

.LBB0_293:
	s_and_b64 vcc, exec, s[6:7]
	s_cbranch_vccz .LBB0_261
	s_and_b64 vcc, exec, s[4:5]
	s_cbranch_vccnz .LBB0_406
	s_cmp_lg_u32 s33, 2
	s_cselect_b64 s[6:7], -1, 0
	s_cmp_eq_u32 s33, 2
	s_cselect_b64 s[36:37], -1, 0
	s_and_b64 s[36:37], s[36:37], s[24:25]
	s_andn2_b64 vcc, exec, s[36:37]
	s_mov_b64 s[38:39], -1
	s_cbranch_vccz .LBB0_405
	s_mov_b64 s[36:37], -1
	s_and_b64 vcc, exec, s[6:7]
	s_cbranch_vccz .LBB0_366
	s_lshl_b32 s6, s33, 2
	s_and_b32 s6, s6, 4
	s_or_b32 s15, s6, s50
	s_cmp_gt_u32 s33, 6
	s_mov_b64 s[6:7], -1
	s_cbranch_scc0 .LBB0_363
	s_cmp_gt_u32 s33, 8
	s_cselect_b64 s[36:37], -1, 0
	s_cmp_lt_u32 s33, 9
	v_pk_mul_f32 v[130:131], v[126:127], v[184:185] op_sel_hi:[1,0]
	v_pk_mul_f32 v[132:133], v[124:125], v[184:185] op_sel_hi:[1,0]
	s_cbranch_scc1 .LBB0_300
	v_mul_f32_e32 v128, 0xbfb8aa3b, v132
	v_mul_f32_e32 v129, 0xbfb8aa3b, v133
	v_mul_f32_e32 v134, 0xbfb8aa3b, v130
	v_mul_f32_e32 v135, 0xbfb8aa3b, v131
	v_exp_f32_e32 v128, v128
	v_exp_f32_e32 v129, v129
	v_exp_f32_e32 v134, v134
	v_exp_f32_e32 v135, v135
	v_add_f32_e32 v128, 1.0, v128
	v_add_f32_e32 v129, 1.0, v129
	v_add_f32_e32 v134, 1.0, v134
	v_add_f32_e32 v135, 1.0, v135
	v_rcp_f32_e32 v128, v128
	v_rcp_f32_e32 v134, v134
	v_rcp_f32_e32 v135, v135
	v_rcp_f32_e32 v129, v129
	v_pk_mul_f32 v[130:131], v[130:131], v[134:135]
	v_pk_mul_f32 v[132:133], v[132:133], v[128:129]

.LBB0_363:
	s_and_b64 vcc, exec, s[6:7]
	s_cbranch_vccz .LBB0_365
	v_mov_b32_e32 v133, v203
	s_cmp_lt_u32 s33, 5
	v_lshlrev_b32_e32 v133, 2, v133
	v_cvt_f32_i32_e32 v136, v133
	v_or_b32_e32 v137, 1, v133
	v_cvt_f32_i32_e32 v138, v137
	s_cselect_b64 s[6:7], -1, 0
	v_and_b32_e32 v131, 0xfcf, v176
	v_cmp_gt_i32_e32 vcc, s53, v176
	v_mul_f32_e32 v136, 0xbedb7629, v136
	v_cndmask_b32_e64 v130, v217, 1.0, s[6:7]
	s_and_b64 s[6:7], s[6:7], exec
	v_cndmask_b32_e32 v131, v208, v131, vcc
	v_exp_f32_e32 v139, v136
	v_mul_f32_e32 v138, 0xbedb7629, v138
	s_mov_b32 s6, 0x95a4000
	v_cvt_f32_u32_e32 v131, v131
	v_exp_f32_e32 v138, v138
	s_cselect_b32 s6, s6, 0xb6a4000
	s_add_u32 s6, s22, s6
	s_addc_u32 s7, s23, 0
	s_lshl_b32 s15, s15, 7
	v_mul_f32_e32 v139, 0.15915494, v139
	s_xor_b32 s15, s15, 0x200
	v_mul_f32_e32 v139, v139, v131
	v_mul_f32_e32 v138, 0.15915494, v138
	s_add_u32 s6, s6, s15
	v_fract_f32_e32 v139, v139
	v_mul_f32_e32 v138, v138, v131
	s_addc_u32 s7, s7, 0
	v_lshlrev_b32_e32 v148, 1, v150
	v_fract_f32_e32 v141, v138
	v_sin_f32_e32 v138, v139
	v_lshl_add_u64 v[128:129], s[6:7], 0, v[148:149]
	v_cos_f32_e32 v140, v139
	v_sin_f32_e32 v148, v141
	v_mul_f32_e32 v132, v130, v184
	v_cos_f32_e32 v142, v141
	v_pk_mul_f32 v[136:137], v[124:125], v[132:133] op_sel_hi:[1,0]
	v_pk_mul_f32 v[134:135], v[126:127], v[132:133] op_sel_hi:[1,0]
	v_pk_mul_f32 v[138:139], v[136:137], v[138:139] op_sel:[1,0] op_sel_hi:[0,0]
	v_pk_fma_f32 v[200:201], v[136:137], v[140:141], v[138:139] neg_lo:[0,0,1] neg_hi:[0,0,1]
	v_pk_fma_f32 v[136:137], v[136:137], v[140:141], v[138:139] op_sel_hi:[1,0,1]
	v_pk_mul_f32 v[138:139], v[134:135], v[148:149] op_sel:[1,0] op_sel_hi:[0,0]
	v_pk_fma_f32 v[140:141], v[134:135], v[142:143], v[138:139] neg_lo:[0,0,1] neg_hi:[0,0,1]
	v_pk_fma_f32 v[134:135], v[134:135], v[142:143], v[138:139] op_sel_hi:[1,0,1]
	v_or_b32_e32 v136, 3, v133
	v_or_b32_e32 v134, 2, v133
	v_cvt_f32_i32_e32 v134, v134
	v_cvt_f32_i32_e32 v136, v136
	v_pk_mul_f32 v[142:143], v[120:121], v[132:133] op_sel_hi:[1,0]
	v_pk_mul_f32 v[138:139], v[122:123], v[132:133] op_sel_hi:[1,0]
	v_mul_f32_e32 v134, 0xbedb7629, v134
	v_exp_f32_e32 v134, v134
	v_mul_f32_e32 v136, 0xbedb7629, v136
	v_exp_f32_e32 v136, v136
	v_pk_mul_f32 v[228:229], v[116:117], v[132:133] op_sel_hi:[1,0]
	v_mul_f32_e32 v134, 0.15915494, v134
	v_mul_f32_e32 v134, v134, v131
	v_fract_f32_e32 v141, v134
	v_mul_f32_e32 v134, 0.15915494, v136
	v_mul_f32_e32 v134, v134, v131
	v_fract_f32_e32 v169, v134
	v_sin_f32_e32 v134, v141
	v_cos_f32_e32 v136, v141
	v_sin_f32_e32 v222, v169
	v_cos_f32_e32 v148, v169
	v_pk_mul_f32 v[224:225], v[142:143], v[134:135] op_sel:[1,0] op_sel_hi:[0,0]
	v_add_u32_e32 v134, 16, v133
	v_cvt_f32_i32_e32 v134, v134
	v_pk_fma_f32 v[226:227], v[142:143], v[136:137], v[224:225] neg_lo:[0,0,1] neg_hi:[0,0,1]
	v_pk_fma_f32 v[142:143], v[142:143], v[136:137], v[224:225] op_sel_hi:[1,0,1]
	v_add_u32_e32 v136, 17, v133
	v_cvt_f32_i32_e32 v136, v136
	v_mul_f32_e32 v134, 0xbedb7629, v134
	v_exp_f32_e32 v134, v134
	v_pk_mul_f32 v[222:223], v[138:139], v[222:223] op_sel:[1,0] op_sel_hi:[0,0]
	v_mul_f32_e32 v136, 0xbedb7629, v136
	v_exp_f32_e32 v136, v136
	v_mul_f32_e32 v134, 0.15915494, v134
	v_pk_fma_f32 v[224:225], v[138:139], v[148:149], v[222:223] neg_lo:[0,0,1] neg_hi:[0,0,1]
	v_pk_fma_f32 v[138:139], v[138:139], v[148:149], v[222:223] op_sel_hi:[1,0,1]
	v_mul_f32_e32 v134, v134, v131
	v_fract_f32_e32 v138, v134
	v_mul_f32_e32 v134, 0.15915494, v136
	v_mul_f32_e32 v134, v134, v131
	v_fract_f32_e32 v141, v134
	v_sin_f32_e32 v134, v138
	v_cos_f32_e32 v136, v138
	v_sin_f32_e32 v142, v141
	v_cos_f32_e32 v138, v141
	v_pk_mul_f32 v[222:223], v[118:119], v[132:133] op_sel_hi:[1,0]
	v_pk_mul_f32 v[230:231], v[228:229], v[134:135] op_sel:[1,0] op_sel_hi:[0,0]
	v_add_u32_e32 v134, 18, v133
	v_pk_fma_f32 v[232:233], v[228:229], v[136:137], v[230:231] neg_lo:[0,0,1] neg_hi:[0,0,1]
	v_pk_fma_f32 v[228:229], v[228:229], v[136:137], v[230:231] op_sel_hi:[1,0,1]
	v_pk_mul_f32 v[230:231], v[222:223], v[142:143] op_sel:[1,0] op_sel_hi:[0,0]
	v_cvt_f32_i32_e32 v134, v134
	v_pk_fma_f32 v[234:235], v[222:223], v[138:139], v[230:231] neg_lo:[0,0,1] neg_hi:[0,0,1]
	v_pk_fma_f32 v[222:223], v[222:223], v[138:139], v[230:231] op_sel_hi:[1,0,1]
	v_pk_mul_f32 v[230:231], v[114:115], v[132:133] op_sel_hi:[1,0]
	v_add_u32_e32 v133, 19, v133
	v_cvt_f32_i32_e32 v136, v133
	v_mul_f32_e32 v133, 0xbedb7629, v134
	v_exp_f32_e32 v134, v133
	v_pk_mul_f32 v[132:133], v[112:113], v[132:133] op_sel_hi:[1,0]
	v_mul_f32_e32 v136, 0xbedb7629, v136
	v_exp_f32_e32 v136, v136
	v_mul_f32_e32 v134, 0.15915494, v134
	v_mul_f32_e32 v134, v134, v131
	v_fract_f32_e32 v138, v134
	v_mul_f32_e32 v134, 0.15915494, v136
	v_mul_f32_e32 v131, v134, v131
	v_fract_f32_e32 v131, v131
	v_sin_f32_e32 v134, v138
	v_cos_f32_e32 v136, v138
	v_sin_f32_e32 v142, v131
	v_cos_f32_e32 v138, v131
	v_pk_mul_f32 v[236:237], v[132:133], v[134:135] op_sel:[1,0] op_sel_hi:[0,0]
	v_pk_fma_f32 v[238:239], v[132:133], v[136:137], v[236:237] neg_lo:[0,0,1] neg_hi:[0,0,1]
	v_pk_fma_f32 v[236:237], v[132:133], v[136:137], v[236:237] op_sel_hi:[1,0,1]
	v_pk_mul_f32 v[132:133], v[230:231], v[142:143] op_sel:[1,0] op_sel_hi:[0,0]
	v_pk_fma_f32 v[240:241], v[230:231], v[138:139], v[132:133] neg_lo:[0,0,1] neg_hi:[0,0,1]
	v_pk_fma_f32 v[230:231], v[230:231], v[138:139], v[132:133] op_sel_hi:[1,0,1]
	v_lshlrev_b64 v[132:133], 10, v[176:177]
	v_lshl_add_u64 v[242:243], v[128:129], 0, v[132:133]
	v_cvt_pk_bf16_f32 v132, v200, v137
	v_cvt_pk_bf16_f32 v133, v140, v135
	v_cvt_pk_bf16_f32 v134, v226, v143
	v_cvt_pk_bf16_f32 v135, v224, v139
	global_store_dwordx4 v[242:243], v[132:135], off nt
	v_and_b32_e32 v131, 0xfdf, v198
	v_cmp_gt_i32_e32 vcc, s53, v198
	v_cvt_pk_bf16_f32 v132, v232, v229
	v_cvt_pk_bf16_f32 v133, v234, v223
	v_cvt_pk_bf16_f32 v134, v238, v237
	v_cvt_pk_bf16_f32 v135, v240, v231
	global_store_dwordx4 v[242:243], v[132:135], off offset:64 nt
	v_cndmask_b32_e32 v131, v208, v131, vcc
	v_cvt_f32_u32_e32 v131, v131
	v_mov_b32_e32 v133, v203
	v_mul_f32_e32 v132, v130, v182
	v_lshlrev_b32_e32 v133, 2, v133
	v_cvt_f32_i32_e32 v136, v133
	v_or_b32_e32 v137, 1, v133
	v_cvt_f32_i32_e32 v138, v137
	v_pk_mul_f32 v[134:135], v[110:111], v[132:133] op_sel_hi:[1,0]
	v_mul_f32_e32 v136, 0xbedb7629, v136
	v_exp_f32_e32 v139, v136
	v_mul_f32_e32 v138, 0xbedb7629, v138
	v_exp_f32_e32 v138, v138
	v_pk_mul_f32 v[136:137], v[108:109], v[132:133] op_sel_hi:[1,0]
	v_mul_f32_e32 v139, 0.15915494, v139
	v_mul_f32_e32 v139, v139, v131
	v_mul_f32_e32 v138, 0.15915494, v138
	v_fract_f32_e32 v139, v139
	v_mul_f32_e32 v138, v138, v131
	v_fract_f32_e32 v141, v138
	v_sin_f32_e32 v138, v139
	v_cos_f32_e32 v140, v139
	v_sin_f32_e32 v148, v141
	v_cos_f32_e32 v142, v141
	v_pk_mul_f32 v[138:139], v[136:137], v[138:139] op_sel:[1,0] op_sel_hi:[0,0]
	v_pk_fma_f32 v[200:201], v[136:137], v[140:141], v[138:139] neg_lo:[0,0,1] neg_hi:[0,0,1]
	v_pk_fma_f32 v[136:137], v[136:137], v[140:141], v[138:139] op_sel_hi:[1,0,1]
	v_pk_mul_f32 v[138:139], v[134:135], v[148:149] op_sel:[1,0] op_sel_hi:[0,0]
	v_pk_fma_f32 v[140:141], v[134:135], v[142:143], v[138:139] neg_lo:[0,0,1] neg_hi:[0,0,1]
	v_pk_fma_f32 v[134:135], v[134:135], v[142:143], v[138:139] op_sel_hi:[1,0,1]
	v_or_b32_e32 v136, 3, v133
	v_or_b32_e32 v134, 2, v133
	v_cvt_f32_i32_e32 v134, v134
	v_cvt_f32_i32_e32 v136, v136
	v_pk_mul_f32 v[142:143], v[104:105], v[132:133] op_sel_hi:[1,0]
	v_pk_mul_f32 v[138:139], v[106:107], v[132:133] op_sel_hi:[1,0]
	v_mul_f32_e32 v134, 0xbedb7629, v134
	v_exp_f32_e32 v134, v134
	v_mul_f32_e32 v136, 0xbedb7629, v136
	v_exp_f32_e32 v136, v136
	v_pk_mul_f32 v[228:229], v[100:101], v[132:133] op_sel_hi:[1,0]
	v_mul_f32_e32 v134, 0.15915494, v134
	v_mul_f32_e32 v134, v134, v131
	v_fract_f32_e32 v141, v134
	v_mul_f32_e32 v134, 0.15915494, v136
	v_mul_f32_e32 v134, v134, v131
	v_fract_f32_e32 v169, v134
	v_sin_f32_e32 v134, v141
	v_cos_f32_e32 v136, v141
	v_sin_f32_e32 v222, v169
	v_cos_f32_e32 v148, v169
	v_pk_mul_f32 v[224:225], v[142:143], v[134:135] op_sel:[1,0] op_sel_hi:[0,0]
	v_add_u32_e32 v134, 16, v133
	v_cvt_f32_i32_e32 v134, v134
	v_pk_fma_f32 v[226:227], v[142:143], v[136:137], v[224:225] neg_lo:[0,0,1] neg_hi:[0,0,1]
	v_pk_fma_f32 v[142:143], v[142:143], v[136:137], v[224:225] op_sel_hi:[1,0,1]
	v_add_u32_e32 v136, 17, v133
	v_cvt_f32_i32_e32 v136, v136
	v_mul_f32_e32 v134, 0xbedb7629, v134
	v_exp_f32_e32 v134, v134
	v_pk_mul_f32 v[222:223], v[138:139], v[222:223] op_sel:[1,0] op_sel_hi:[0,0]
	v_mul_f32_e32 v136, 0xbedb7629, v136
	v_exp_f32_e32 v136, v136
	v_mul_f32_e32 v134, 0.15915494, v134
	v_pk_fma_f32 v[224:225], v[138:139], v[148:149], v[222:223] neg_lo:[0,0,1] neg_hi:[0,0,1]
	v_pk_fma_f32 v[138:139], v[138:139], v[148:149], v[222:223] op_sel_hi:[1,0,1]
	v_mul_f32_e32 v134, v134, v131
	v_fract_f32_e32 v138, v134
	v_mul_f32_e32 v134, 0.15915494, v136
	v_mul_f32_e32 v134, v134, v131
	v_fract_f32_e32 v141, v134
	v_sin_f32_e32 v134, v138
	v_cos_f32_e32 v136, v138
	v_sin_f32_e32 v142, v141
	v_cos_f32_e32 v138, v141
	v_pk_mul_f32 v[222:223], v[102:103], v[132:133] op_sel_hi:[1,0]
	v_pk_mul_f32 v[230:231], v[228:229], v[134:135] op_sel:[1,0] op_sel_hi:[0,0]
	v_add_u32_e32 v134, 18, v133
	v_pk_fma_f32 v[232:233], v[228:229], v[136:137], v[230:231] neg_lo:[0,0,1] neg_hi:[0,0,1]
	v_pk_fma_f32 v[228:229], v[228:229], v[136:137], v[230:231] op_sel_hi:[1,0,1]
	v_pk_mul_f32 v[230:231], v[222:223], v[142:143] op_sel:[1,0] op_sel_hi:[0,0]
	v_cvt_f32_i32_e32 v134, v134
	v_pk_fma_f32 v[234:235], v[222:223], v[138:139], v[230:231] neg_lo:[0,0,1] neg_hi:[0,0,1]
	v_pk_fma_f32 v[222:223], v[222:223], v[138:139], v[230:231] op_sel_hi:[1,0,1]
	v_pk_mul_f32 v[230:231], v[98:99], v[132:133] op_sel_hi:[1,0]
	v_add_u32_e32 v133, 19, v133
	v_cvt_f32_i32_e32 v136, v133
	v_mul_f32_e32 v133, 0xbedb7629, v134
	v_exp_f32_e32 v134, v133
	v_pk_mul_f32 v[132:133], v[96:97], v[132:133] op_sel_hi:[1,0]
	v_mul_f32_e32 v136, 0xbedb7629, v136
	v_exp_f32_e32 v136, v136
	v_mul_f32_e32 v134, 0.15915494, v134
	v_mul_f32_e32 v134, v134, v131
	v_fract_f32_e32 v138, v134
	v_mul_f32_e32 v134, 0.15915494, v136
	v_mul_f32_e32 v131, v134, v131
	v_fract_f32_e32 v131, v131
	v_sin_f32_e32 v134, v138
	v_cos_f32_e32 v136, v138
	v_sin_f32_e32 v142, v131
	v_cos_f32_e32 v138, v131
	v_pk_mul_f32 v[236:237], v[132:133], v[134:135] op_sel:[1,0] op_sel_hi:[0,0]
	v_pk_fma_f32 v[238:239], v[132:133], v[136:137], v[236:237] neg_lo:[0,0,1] neg_hi:[0,0,1]
	v_pk_fma_f32 v[236:237], v[132:133], v[136:137], v[236:237] op_sel_hi:[1,0,1]
	v_pk_mul_f32 v[132:133], v[230:231], v[142:143] op_sel:[1,0] op_sel_hi:[0,0]
	v_pk_fma_f32 v[240:241], v[230:231], v[138:139], v[132:133] neg_lo:[0,0,1] neg_hi:[0,0,1]
	v_pk_fma_f32 v[230:231], v[230:231], v[138:139], v[132:133] op_sel_hi:[1,0,1]
	v_lshlrev_b64 v[132:133], 10, v[198:199]
	v_lshl_add_u64 v[198:199], v[128:129], 0, v[132:133]
	v_cvt_pk_bf16_f32 v132, v200, v137
	v_cvt_pk_bf16_f32 v133, v140, v135
	v_cvt_pk_bf16_f32 v134, v226, v143
	v_cvt_pk_bf16_f32 v135, v224, v139
	global_store_dwordx4 v[198:199], v[132:135], off nt
	v_and_b32_e32 v131, 0xfef, v196
	v_cmp_gt_i32_e32 vcc, s53, v196
	v_cvt_pk_bf16_f32 v132, v232, v229
	v_cvt_pk_bf16_f32 v133, v234, v223
	v_cvt_pk_bf16_f32 v134, v238, v237
	v_cvt_pk_bf16_f32 v135, v240, v231
	global_store_dwordx4 v[198:199], v[132:135], off offset:64 nt
	v_cndmask_b32_e32 v131, v208, v131, vcc
	v_cvt_f32_u32_e32 v131, v131
	v_mov_b32_e32 v133, v203
	v_mul_f32_e32 v132, v130, v180
	v_lshlrev_b32_e32 v133, 2, v133
	v_cvt_f32_i32_e32 v136, v133
	v_or_b32_e32 v137, 1, v133
	v_cvt_f32_i32_e32 v138, v137
	v_pk_mul_f32 v[134:135], v[94:95], v[132:133] op_sel_hi:[1,0]
	v_mul_f32_e32 v136, 0xbedb7629, v136
	v_exp_f32_e32 v139, v136
	v_mul_f32_e32 v138, 0xbedb7629, v138
	v_exp_f32_e32 v138, v138
	v_pk_mul_f32 v[136:137], v[92:93], v[132:133] op_sel_hi:[1,0]
	v_mul_f32_e32 v139, 0.15915494, v139
	v_mul_f32_e32 v139, v139, v131
	v_mul_f32_e32 v138, 0.15915494, v138
	v_fract_f32_e32 v139, v139
	v_mul_f32_e32 v138, v138, v131
	v_fract_f32_e32 v141, v138
	v_sin_f32_e32 v138, v139
	v_cos_f32_e32 v140, v139
	v_sin_f32_e32 v148, v141
	v_cos_f32_e32 v142, v141
	v_pk_mul_f32 v[138:139], v[136:137], v[138:139] op_sel:[1,0] op_sel_hi:[0,0]
	v_pk_fma_f32 v[198:199], v[136:137], v[140:141], v[138:139] neg_lo:[0,0,1] neg_hi:[0,0,1]
	v_pk_fma_f32 v[136:137], v[136:137], v[140:141], v[138:139] op_sel_hi:[1,0,1]
	v_pk_mul_f32 v[138:139], v[134:135], v[148:149] op_sel:[1,0] op_sel_hi:[0,0]
	v_pk_fma_f32 v[140:141], v[134:135], v[142:143], v[138:139] neg_lo:[0,0,1] neg_hi:[0,0,1]
	v_pk_fma_f32 v[134:135], v[134:135], v[142:143], v[138:139] op_sel_hi:[1,0,1]
	v_or_b32_e32 v136, 3, v133
	v_or_b32_e32 v134, 2, v133
	v_cvt_f32_i32_e32 v134, v134
	v_cvt_f32_i32_e32 v136, v136
	v_pk_mul_f32 v[142:143], v[88:89], v[132:133] op_sel_hi:[1,0]
	v_pk_mul_f32 v[138:139], v[90:91], v[132:133] op_sel_hi:[1,0]
	v_mul_f32_e32 v134, 0xbedb7629, v134
	v_exp_f32_e32 v134, v134
	v_mul_f32_e32 v136, 0xbedb7629, v136
	v_exp_f32_e32 v136, v136
	v_pk_mul_f32 v[226:227], v[84:85], v[132:133] op_sel_hi:[1,0]
	v_mul_f32_e32 v134, 0.15915494, v134
	v_mul_f32_e32 v134, v134, v131
	v_fract_f32_e32 v141, v134
	v_mul_f32_e32 v134, 0.15915494, v136
	v_mul_f32_e32 v134, v134, v131
	v_fract_f32_e32 v169, v134
	v_sin_f32_e32 v134, v141
	v_cos_f32_e32 v136, v141
	v_sin_f32_e32 v200, v169
	v_cos_f32_e32 v148, v169
	v_pk_mul_f32 v[222:223], v[142:143], v[134:135] op_sel:[1,0] op_sel_hi:[0,0]
	v_add_u32_e32 v134, 16, v133
	v_cvt_f32_i32_e32 v134, v134
	v_pk_fma_f32 v[224:225], v[142:143], v[136:137], v[222:223] neg_lo:[0,0,1] neg_hi:[0,0,1]
	v_pk_fma_f32 v[142:143], v[142:143], v[136:137], v[222:223] op_sel_hi:[1,0,1]
	v_add_u32_e32 v136, 17, v133
	v_cvt_f32_i32_e32 v136, v136
	v_mul_f32_e32 v134, 0xbedb7629, v134
	v_exp_f32_e32 v134, v134
	v_pk_mul_f32 v[200:201], v[138:139], v[200:201] op_sel:[1,0] op_sel_hi:[0,0]
	v_mul_f32_e32 v136, 0xbedb7629, v136
	v_exp_f32_e32 v136, v136
	v_mul_f32_e32 v134, 0.15915494, v134
	v_pk_fma_f32 v[222:223], v[138:139], v[148:149], v[200:201] neg_lo:[0,0,1] neg_hi:[0,0,1]
	v_pk_fma_f32 v[138:139], v[138:139], v[148:149], v[200:201] op_sel_hi:[1,0,1]
	v_mul_f32_e32 v134, v134, v131
	v_fract_f32_e32 v138, v134
	v_mul_f32_e32 v134, 0.15915494, v136
	v_mul_f32_e32 v134, v134, v131
	v_fract_f32_e32 v141, v134
	v_sin_f32_e32 v134, v138
	v_cos_f32_e32 v136, v138
	v_sin_f32_e32 v142, v141
	v_cos_f32_e32 v138, v141
	v_pk_mul_f32 v[200:201], v[86:87], v[132:133] op_sel_hi:[1,0]
	v_pk_mul_f32 v[228:229], v[226:227], v[134:135] op_sel:[1,0] op_sel_hi:[0,0]
	v_add_u32_e32 v134, 18, v133
	v_pk_fma_f32 v[230:231], v[226:227], v[136:137], v[228:229] neg_lo:[0,0,1] neg_hi:[0,0,1]
	v_pk_fma_f32 v[226:227], v[226:227], v[136:137], v[228:229] op_sel_hi:[1,0,1]
	v_pk_mul_f32 v[228:229], v[200:201], v[142:143] op_sel:[1,0] op_sel_hi:[0,0]
	v_cvt_f32_i32_e32 v134, v134
	v_pk_fma_f32 v[232:233], v[200:201], v[138:139], v[228:229] neg_lo:[0,0,1] neg_hi:[0,0,1]
	v_pk_fma_f32 v[200:201], v[200:201], v[138:139], v[228:229] op_sel_hi:[1,0,1]
	v_pk_mul_f32 v[228:229], v[82:83], v[132:133] op_sel_hi:[1,0]
	v_add_u32_e32 v133, 19, v133
	v_cvt_f32_i32_e32 v136, v133
	v_mul_f32_e32 v133, 0xbedb7629, v134
	v_exp_f32_e32 v134, v133
	v_pk_mul_f32 v[132:133], v[80:81], v[132:133] op_sel_hi:[1,0]
	v_mul_f32_e32 v136, 0xbedb7629, v136
	v_exp_f32_e32 v136, v136
	v_mul_f32_e32 v134, 0.15915494, v134
	v_mul_f32_e32 v134, v134, v131
	v_fract_f32_e32 v138, v134
	v_mul_f32_e32 v134, 0.15915494, v136
	v_mul_f32_e32 v131, v134, v131
	v_fract_f32_e32 v131, v131
	v_sin_f32_e32 v134, v138
	v_cos_f32_e32 v136, v138
	v_sin_f32_e32 v142, v131
	v_cos_f32_e32 v138, v131
	v_pk_mul_f32 v[234:235], v[132:133], v[134:135] op_sel:[1,0] op_sel_hi:[0,0]
	v_pk_fma_f32 v[236:237], v[132:133], v[136:137], v[234:235] neg_lo:[0,0,1] neg_hi:[0,0,1]
	v_pk_fma_f32 v[234:235], v[132:133], v[136:137], v[234:235] op_sel_hi:[1,0,1]
	v_pk_mul_f32 v[132:133], v[228:229], v[142:143] op_sel:[1,0] op_sel_hi:[0,0]
	v_pk_fma_f32 v[238:239], v[228:229], v[138:139], v[132:133] neg_lo:[0,0,1] neg_hi:[0,0,1]
	v_pk_fma_f32 v[228:229], v[228:229], v[138:139], v[132:133] op_sel_hi:[1,0,1]
	v_lshlrev_b64 v[132:133], 10, v[196:197]
	v_lshl_add_u64 v[196:197], v[128:129], 0, v[132:133]
	v_cvt_pk_bf16_f32 v132, v198, v137
	v_cvt_pk_bf16_f32 v133, v140, v135
	v_cvt_pk_bf16_f32 v134, v224, v143
	v_cvt_pk_bf16_f32 v135, v222, v139
	global_store_dwordx4 v[196:197], v[132:135], off nt
	v_and_b32_e32 v131, 0xfff, v194
	v_cmp_gt_i32_e32 vcc, s53, v194
	v_cvt_pk_bf16_f32 v132, v230, v227
	v_cvt_pk_bf16_f32 v133, v232, v201
	v_cvt_pk_bf16_f32 v134, v236, v235
	v_cvt_pk_bf16_f32 v135, v238, v229
	global_store_dwordx4 v[196:197], v[132:135], off offset:64 nt
	v_cndmask_b32_e32 v131, v208, v131, vcc
	v_cvt_f32_u32_e32 v131, v131
	v_mov_b32_e32 v133, v203
	v_mul_f32_e32 v132, v130, v178
	v_lshlrev_b32_e32 v133, 2, v133
	v_cvt_f32_i32_e32 v136, v133
	v_or_b32_e32 v137, 1, v133
	v_cvt_f32_i32_e32 v138, v137
	v_pk_mul_f32 v[134:135], v[78:79], v[132:133] op_sel_hi:[1,0]
	v_mul_f32_e32 v136, 0xbedb7629, v136
	v_exp_f32_e32 v139, v136
	v_mul_f32_e32 v138, 0xbedb7629, v138
	v_exp_f32_e32 v138, v138
	v_pk_mul_f32 v[136:137], v[76:77], v[132:133] op_sel_hi:[1,0]
	v_mul_f32_e32 v139, 0.15915494, v139
	v_mul_f32_e32 v139, v139, v131
	v_mul_f32_e32 v138, 0.15915494, v138
	v_fract_f32_e32 v139, v139
	v_mul_f32_e32 v138, v138, v131
	v_fract_f32_e32 v141, v138
	v_sin_f32_e32 v138, v139
	v_cos_f32_e32 v140, v139
	v_sin_f32_e32 v148, v141
	v_cos_f32_e32 v142, v141
	v_pk_mul_f32 v[138:139], v[136:137], v[138:139] op_sel:[1,0] op_sel_hi:[0,0]
	v_pk_fma_f32 v[196:197], v[136:137], v[140:141], v[138:139] neg_lo:[0,0,1] neg_hi:[0,0,1]
	v_pk_fma_f32 v[136:137], v[136:137], v[140:141], v[138:139] op_sel_hi:[1,0,1]
	v_pk_mul_f32 v[138:139], v[134:135], v[148:149] op_sel:[1,0] op_sel_hi:[0,0]
	v_pk_fma_f32 v[140:141], v[134:135], v[142:143], v[138:139] neg_lo:[0,0,1] neg_hi:[0,0,1]
	v_pk_fma_f32 v[134:135], v[134:135], v[142:143], v[138:139] op_sel_hi:[1,0,1]
	v_or_b32_e32 v136, 3, v133
	v_or_b32_e32 v134, 2, v133
	v_cvt_f32_i32_e32 v134, v134
	v_cvt_f32_i32_e32 v136, v136
	v_pk_mul_f32 v[142:143], v[72:73], v[132:133] op_sel_hi:[1,0]
	v_pk_mul_f32 v[138:139], v[74:75], v[132:133] op_sel_hi:[1,0]
	v_mul_f32_e32 v134, 0xbedb7629, v134
	v_exp_f32_e32 v134, v134
	v_mul_f32_e32 v136, 0xbedb7629, v136
	v_exp_f32_e32 v136, v136
	v_pk_mul_f32 v[224:225], v[68:69], v[132:133] op_sel_hi:[1,0]
	v_mul_f32_e32 v134, 0.15915494, v134
	v_mul_f32_e32 v134, v134, v131
	v_fract_f32_e32 v141, v134
	v_mul_f32_e32 v134, 0.15915494, v136
	v_mul_f32_e32 v134, v134, v131
	v_fract_f32_e32 v169, v134
	v_sin_f32_e32 v134, v141
	v_cos_f32_e32 v136, v141
	v_sin_f32_e32 v198, v169
	v_cos_f32_e32 v148, v169
	v_pk_mul_f32 v[200:201], v[142:143], v[134:135] op_sel:[1,0] op_sel_hi:[0,0]
	v_add_u32_e32 v134, 16, v133
	v_cvt_f32_i32_e32 v134, v134
	v_pk_fma_f32 v[222:223], v[142:143], v[136:137], v[200:201] neg_lo:[0,0,1] neg_hi:[0,0,1]
	v_pk_fma_f32 v[142:143], v[142:143], v[136:137], v[200:201] op_sel_hi:[1,0,1]
	v_add_u32_e32 v136, 17, v133
	v_cvt_f32_i32_e32 v136, v136
	v_mul_f32_e32 v134, 0xbedb7629, v134
	v_exp_f32_e32 v134, v134
	v_pk_mul_f32 v[198:199], v[138:139], v[198:199] op_sel:[1,0] op_sel_hi:[0,0]
	v_mul_f32_e32 v136, 0xbedb7629, v136
	v_exp_f32_e32 v136, v136
	v_mul_f32_e32 v134, 0.15915494, v134
	v_pk_fma_f32 v[200:201], v[138:139], v[148:149], v[198:199] neg_lo:[0,0,1] neg_hi:[0,0,1]
	v_pk_fma_f32 v[138:139], v[138:139], v[148:149], v[198:199] op_sel_hi:[1,0,1]
	v_mul_f32_e32 v134, v134, v131
	v_fract_f32_e32 v138, v134
	v_mul_f32_e32 v134, 0.15915494, v136
	v_mul_f32_e32 v134, v134, v131
	v_fract_f32_e32 v141, v134
	v_sin_f32_e32 v134, v138
	v_cos_f32_e32 v136, v138
	v_sin_f32_e32 v142, v141
	v_cos_f32_e32 v138, v141
	v_pk_mul_f32 v[198:199], v[70:71], v[132:133] op_sel_hi:[1,0]
	v_pk_mul_f32 v[226:227], v[224:225], v[134:135] op_sel:[1,0] op_sel_hi:[0,0]
	v_add_u32_e32 v134, 18, v133
	v_pk_fma_f32 v[228:229], v[224:225], v[136:137], v[226:227] neg_lo:[0,0,1] neg_hi:[0,0,1]
	v_pk_fma_f32 v[224:225], v[224:225], v[136:137], v[226:227] op_sel_hi:[1,0,1]
	v_pk_mul_f32 v[226:227], v[198:199], v[142:143] op_sel:[1,0] op_sel_hi:[0,0]
	v_cvt_f32_i32_e32 v134, v134
	v_pk_fma_f32 v[230:231], v[198:199], v[138:139], v[226:227] neg_lo:[0,0,1] neg_hi:[0,0,1]
	v_pk_fma_f32 v[198:199], v[198:199], v[138:139], v[226:227] op_sel_hi:[1,0,1]
	v_pk_mul_f32 v[226:227], v[66:67], v[132:133] op_sel_hi:[1,0]
	v_add_u32_e32 v133, 19, v133
	v_cvt_f32_i32_e32 v136, v133
	v_mul_f32_e32 v133, 0xbedb7629, v134
	v_exp_f32_e32 v134, v133
	v_pk_mul_f32 v[132:133], v[64:65], v[132:133] op_sel_hi:[1,0]
	v_mul_f32_e32 v136, 0xbedb7629, v136
	v_exp_f32_e32 v136, v136
	v_mul_f32_e32 v134, 0.15915494, v134
	v_mul_f32_e32 v134, v134, v131
	v_fract_f32_e32 v138, v134
	v_mul_f32_e32 v134, 0.15915494, v136
	v_mul_f32_e32 v131, v134, v131
	v_fract_f32_e32 v131, v131
	v_sin_f32_e32 v134, v138
	v_cos_f32_e32 v136, v138
	v_sin_f32_e32 v142, v131
	v_cos_f32_e32 v138, v131
	v_pk_mul_f32 v[232:233], v[132:133], v[134:135] op_sel:[1,0] op_sel_hi:[0,0]
	v_pk_fma_f32 v[234:235], v[132:133], v[136:137], v[232:233] neg_lo:[0,0,1] neg_hi:[0,0,1]
	v_pk_fma_f32 v[232:233], v[132:133], v[136:137], v[232:233] op_sel_hi:[1,0,1]
	v_pk_mul_f32 v[132:133], v[226:227], v[142:143] op_sel:[1,0] op_sel_hi:[0,0]
	v_pk_fma_f32 v[236:237], v[226:227], v[138:139], v[132:133] neg_lo:[0,0,1] neg_hi:[0,0,1]
	v_pk_fma_f32 v[226:227], v[226:227], v[138:139], v[132:133] op_sel_hi:[1,0,1]
	v_lshlrev_b64 v[132:133], 10, v[194:195]
	v_lshl_add_u64 v[194:195], v[128:129], 0, v[132:133]
	v_cvt_pk_bf16_f32 v132, v196, v137
	v_cvt_pk_bf16_f32 v133, v140, v135
	v_cvt_pk_bf16_f32 v134, v222, v143
	v_cvt_pk_bf16_f32 v135, v200, v139
	global_store_dwordx4 v[194:195], v[132:135], off nt
	v_and_b32_e32 v131, 0xfcf, v192
	v_cmp_gt_i32_e32 vcc, s53, v192
	v_cvt_pk_bf16_f32 v132, v228, v225
	v_cvt_pk_bf16_f32 v133, v230, v199
	v_cvt_pk_bf16_f32 v134, v234, v233
	v_cvt_pk_bf16_f32 v135, v236, v227
	global_store_dwordx4 v[194:195], v[132:135], off offset:64 nt
	v_cndmask_b32_e32 v131, v208, v131, vcc
	v_cvt_f32_u32_e32 v131, v131
	v_mov_b32_e32 v133, v203
	v_mul_f32_e32 v132, v130, v174
	v_lshlrev_b32_e32 v133, 2, v133
	v_cvt_f32_i32_e32 v136, v133
	v_or_b32_e32 v137, 1, v133
	v_cvt_f32_i32_e32 v138, v137
	v_pk_mul_f32 v[134:135], v[62:63], v[132:133] op_sel_hi:[1,0]
	v_mul_f32_e32 v136, 0xbedb7629, v136
	v_exp_f32_e32 v139, v136
	v_mul_f32_e32 v138, 0xbedb7629, v138
	v_exp_f32_e32 v138, v138
	v_pk_mul_f32 v[136:137], v[60:61], v[132:133] op_sel_hi:[1,0]
	v_mul_f32_e32 v139, 0.15915494, v139
	v_mul_f32_e32 v139, v139, v131
	v_mul_f32_e32 v138, 0.15915494, v138
	v_fract_f32_e32 v139, v139
	v_mul_f32_e32 v138, v138, v131
	v_fract_f32_e32 v141, v138
	v_sin_f32_e32 v138, v139
	v_cos_f32_e32 v140, v139
	v_sin_f32_e32 v148, v141
	v_cos_f32_e32 v142, v141
	v_pk_mul_f32 v[138:139], v[136:137], v[138:139] op_sel:[1,0] op_sel_hi:[0,0]
	v_pk_fma_f32 v[194:195], v[136:137], v[140:141], v[138:139] neg_lo:[0,0,1] neg_hi:[0,0,1]
	v_pk_fma_f32 v[136:137], v[136:137], v[140:141], v[138:139] op_sel_hi:[1,0,1]
	v_pk_mul_f32 v[138:139], v[134:135], v[148:149] op_sel:[1,0] op_sel_hi:[0,0]
	v_pk_fma_f32 v[140:141], v[134:135], v[142:143], v[138:139] neg_lo:[0,0,1] neg_hi:[0,0,1]
	v_pk_fma_f32 v[134:135], v[134:135], v[142:143], v[138:139] op_sel_hi:[1,0,1]
	v_or_b32_e32 v136, 3, v133
	v_or_b32_e32 v134, 2, v133
	v_cvt_f32_i32_e32 v134, v134
	v_cvt_f32_i32_e32 v136, v136
	v_pk_mul_f32 v[142:143], v[56:57], v[132:133] op_sel_hi:[1,0]
	v_pk_mul_f32 v[138:139], v[58:59], v[132:133] op_sel_hi:[1,0]
	v_mul_f32_e32 v134, 0xbedb7629, v134
	v_exp_f32_e32 v134, v134
	v_mul_f32_e32 v136, 0xbedb7629, v136
	v_exp_f32_e32 v136, v136
	v_pk_mul_f32 v[222:223], v[52:53], v[132:133] op_sel_hi:[1,0]
	v_mul_f32_e32 v134, 0.15915494, v134
	v_mul_f32_e32 v134, v134, v131
	v_fract_f32_e32 v141, v134
	v_mul_f32_e32 v134, 0.15915494, v136
	v_mul_f32_e32 v134, v134, v131
	v_fract_f32_e32 v169, v134
	v_sin_f32_e32 v134, v141
	v_cos_f32_e32 v136, v141
	v_sin_f32_e32 v196, v169
	v_cos_f32_e32 v148, v169
	v_pk_mul_f32 v[198:199], v[142:143], v[134:135] op_sel:[1,0] op_sel_hi:[0,0]
	v_add_u32_e32 v134, 16, v133
	v_cvt_f32_i32_e32 v134, v134
	v_pk_fma_f32 v[200:201], v[142:143], v[136:137], v[198:199] neg_lo:[0,0,1] neg_hi:[0,0,1]
	v_pk_fma_f32 v[142:143], v[142:143], v[136:137], v[198:199] op_sel_hi:[1,0,1]
	v_add_u32_e32 v136, 17, v133
	v_cvt_f32_i32_e32 v136, v136
	v_mul_f32_e32 v134, 0xbedb7629, v134
	v_exp_f32_e32 v134, v134
	v_pk_mul_f32 v[196:197], v[138:139], v[196:197] op_sel:[1,0] op_sel_hi:[0,0]
	v_mul_f32_e32 v136, 0xbedb7629, v136
	v_exp_f32_e32 v136, v136
	v_mul_f32_e32 v134, 0.15915494, v134
	v_pk_fma_f32 v[198:199], v[138:139], v[148:149], v[196:197] neg_lo:[0,0,1] neg_hi:[0,0,1]
	v_pk_fma_f32 v[138:139], v[138:139], v[148:149], v[196:197] op_sel_hi:[1,0,1]
	v_mul_f32_e32 v134, v134, v131
	v_fract_f32_e32 v138, v134
	v_mul_f32_e32 v134, 0.15915494, v136
	v_mul_f32_e32 v134, v134, v131
	v_fract_f32_e32 v141, v134
	v_sin_f32_e32 v134, v138
	v_cos_f32_e32 v136, v138
	v_sin_f32_e32 v142, v141
	v_cos_f32_e32 v138, v141
	v_pk_mul_f32 v[196:197], v[54:55], v[132:133] op_sel_hi:[1,0]
	v_pk_mul_f32 v[224:225], v[222:223], v[134:135] op_sel:[1,0] op_sel_hi:[0,0]
	v_add_u32_e32 v134, 18, v133
	v_pk_fma_f32 v[226:227], v[222:223], v[136:137], v[224:225] neg_lo:[0,0,1] neg_hi:[0,0,1]
	v_pk_fma_f32 v[222:223], v[222:223], v[136:137], v[224:225] op_sel_hi:[1,0,1]
	v_pk_mul_f32 v[224:225], v[196:197], v[142:143] op_sel:[1,0] op_sel_hi:[0,0]
	v_cvt_f32_i32_e32 v134, v134
	v_pk_fma_f32 v[228:229], v[196:197], v[138:139], v[224:225] neg_lo:[0,0,1] neg_hi:[0,0,1]
	v_pk_fma_f32 v[196:197], v[196:197], v[138:139], v[224:225] op_sel_hi:[1,0,1]
	v_pk_mul_f32 v[224:225], v[50:51], v[132:133] op_sel_hi:[1,0]
	v_add_u32_e32 v133, 19, v133
	v_cvt_f32_i32_e32 v136, v133
	v_mul_f32_e32 v133, 0xbedb7629, v134
	v_exp_f32_e32 v134, v133
	v_pk_mul_f32 v[132:133], v[48:49], v[132:133] op_sel_hi:[1,0]
	v_mul_f32_e32 v136, 0xbedb7629, v136
	v_exp_f32_e32 v136, v136
	v_mul_f32_e32 v134, 0.15915494, v134
	v_mul_f32_e32 v134, v134, v131
	v_fract_f32_e32 v138, v134
	v_mul_f32_e32 v134, 0.15915494, v136
	v_mul_f32_e32 v131, v134, v131
	v_fract_f32_e32 v131, v131
	v_sin_f32_e32 v134, v138
	v_cos_f32_e32 v136, v138
	v_sin_f32_e32 v142, v131
	v_cos_f32_e32 v138, v131
	v_pk_mul_f32 v[230:231], v[132:133], v[134:135] op_sel:[1,0] op_sel_hi:[0,0]
	v_pk_fma_f32 v[232:233], v[132:133], v[136:137], v[230:231] neg_lo:[0,0,1] neg_hi:[0,0,1]
	v_pk_fma_f32 v[230:231], v[132:133], v[136:137], v[230:231] op_sel_hi:[1,0,1]
	v_pk_mul_f32 v[132:133], v[224:225], v[142:143] op_sel:[1,0] op_sel_hi:[0,0]
	v_pk_fma_f32 v[234:235], v[224:225], v[138:139], v[132:133] neg_lo:[0,0,1] neg_hi:[0,0,1]
	v_pk_fma_f32 v[224:225], v[224:225], v[138:139], v[132:133] op_sel_hi:[1,0,1]
	v_lshlrev_b64 v[132:133], 10, v[192:193]
	v_lshl_add_u64 v[192:193], v[128:129], 0, v[132:133]
	v_cvt_pk_bf16_f32 v132, v194, v137
	v_cvt_pk_bf16_f32 v133, v140, v135
	v_cvt_pk_bf16_f32 v134, v200, v143
	v_cvt_pk_bf16_f32 v135, v198, v139
	global_store_dwordx4 v[192:193], v[132:135], off nt
	v_and_b32_e32 v131, 0xfdf, v190
	v_cmp_gt_i32_e32 vcc, s53, v190
	v_cvt_pk_bf16_f32 v132, v226, v223
	v_cvt_pk_bf16_f32 v133, v228, v197
	v_cvt_pk_bf16_f32 v134, v232, v231
	v_cvt_pk_bf16_f32 v135, v234, v225
	global_store_dwordx4 v[192:193], v[132:135], off offset:64 nt
	v_cndmask_b32_e32 v131, v208, v131, vcc
	v_cvt_f32_u32_e32 v131, v131
	v_mov_b32_e32 v133, v203
	v_mul_f32_e32 v132, v130, v172
	v_lshlrev_b32_e32 v133, 2, v133
	v_cvt_f32_i32_e32 v136, v133
	v_or_b32_e32 v137, 1, v133
	v_cvt_f32_i32_e32 v138, v137
	v_pk_mul_f32 v[134:135], v[46:47], v[132:133] op_sel_hi:[1,0]
	v_mul_f32_e32 v136, 0xbedb7629, v136
	v_exp_f32_e32 v139, v136
	v_mul_f32_e32 v138, 0xbedb7629, v138
	v_exp_f32_e32 v138, v138
	v_pk_mul_f32 v[136:137], v[44:45], v[132:133] op_sel_hi:[1,0]
	v_mul_f32_e32 v139, 0.15915494, v139
	v_mul_f32_e32 v139, v139, v131
	v_mul_f32_e32 v138, 0.15915494, v138
	v_fract_f32_e32 v139, v139
	v_mul_f32_e32 v138, v138, v131
	v_fract_f32_e32 v141, v138
	v_sin_f32_e32 v138, v139
	v_cos_f32_e32 v140, v139
	v_sin_f32_e32 v148, v141
	v_cos_f32_e32 v142, v141
	v_pk_mul_f32 v[138:139], v[136:137], v[138:139] op_sel:[1,0] op_sel_hi:[0,0]
	v_pk_fma_f32 v[192:193], v[136:137], v[140:141], v[138:139] neg_lo:[0,0,1] neg_hi:[0,0,1]
	v_pk_fma_f32 v[136:137], v[136:137], v[140:141], v[138:139] op_sel_hi:[1,0,1]
	v_pk_mul_f32 v[138:139], v[134:135], v[148:149] op_sel:[1,0] op_sel_hi:[0,0]
	v_pk_fma_f32 v[140:141], v[134:135], v[142:143], v[138:139] neg_lo:[0,0,1] neg_hi:[0,0,1]
	v_pk_fma_f32 v[134:135], v[134:135], v[142:143], v[138:139] op_sel_hi:[1,0,1]
	v_or_b32_e32 v136, 3, v133
	v_or_b32_e32 v134, 2, v133
	v_cvt_f32_i32_e32 v134, v134
	v_cvt_f32_i32_e32 v136, v136
	v_pk_mul_f32 v[142:143], v[40:41], v[132:133] op_sel_hi:[1,0]
	v_pk_mul_f32 v[138:139], v[42:43], v[132:133] op_sel_hi:[1,0]
	v_mul_f32_e32 v134, 0xbedb7629, v134
	v_exp_f32_e32 v134, v134
	v_mul_f32_e32 v136, 0xbedb7629, v136
	v_exp_f32_e32 v136, v136
	v_pk_mul_f32 v[200:201], v[36:37], v[132:133] op_sel_hi:[1,0]
	v_mul_f32_e32 v134, 0.15915494, v134
	v_mul_f32_e32 v134, v134, v131
	v_fract_f32_e32 v141, v134
	v_mul_f32_e32 v134, 0.15915494, v136
	v_mul_f32_e32 v134, v134, v131
	v_fract_f32_e32 v169, v134
	v_sin_f32_e32 v134, v141
	v_cos_f32_e32 v136, v141
	v_sin_f32_e32 v194, v169
	v_cos_f32_e32 v148, v169
	v_pk_mul_f32 v[196:197], v[142:143], v[134:135] op_sel:[1,0] op_sel_hi:[0,0]
	v_add_u32_e32 v134, 16, v133
	v_cvt_f32_i32_e32 v134, v134
	v_pk_fma_f32 v[198:199], v[142:143], v[136:137], v[196:197] neg_lo:[0,0,1] neg_hi:[0,0,1]
	v_pk_fma_f32 v[142:143], v[142:143], v[136:137], v[196:197] op_sel_hi:[1,0,1]
	v_add_u32_e32 v136, 17, v133
	v_cvt_f32_i32_e32 v136, v136
	v_mul_f32_e32 v134, 0xbedb7629, v134
	v_exp_f32_e32 v134, v134
	v_pk_mul_f32 v[194:195], v[138:139], v[194:195] op_sel:[1,0] op_sel_hi:[0,0]
	v_mul_f32_e32 v136, 0xbedb7629, v136
	v_exp_f32_e32 v136, v136
	v_mul_f32_e32 v134, 0.15915494, v134
	v_pk_fma_f32 v[196:197], v[138:139], v[148:149], v[194:195] neg_lo:[0,0,1] neg_hi:[0,0,1]
	v_pk_fma_f32 v[138:139], v[138:139], v[148:149], v[194:195] op_sel_hi:[1,0,1]
	v_mul_f32_e32 v134, v134, v131
	v_fract_f32_e32 v138, v134
	v_mul_f32_e32 v134, 0.15915494, v136
	v_mul_f32_e32 v134, v134, v131
	v_fract_f32_e32 v141, v134
	v_sin_f32_e32 v134, v138
	v_cos_f32_e32 v136, v138
	v_sin_f32_e32 v142, v141
	v_cos_f32_e32 v138, v141
	v_pk_mul_f32 v[194:195], v[38:39], v[132:133] op_sel_hi:[1,0]
	v_pk_mul_f32 v[222:223], v[200:201], v[134:135] op_sel:[1,0] op_sel_hi:[0,0]
	v_add_u32_e32 v134, 18, v133
	v_pk_fma_f32 v[224:225], v[200:201], v[136:137], v[222:223] neg_lo:[0,0,1] neg_hi:[0,0,1]
	v_pk_fma_f32 v[200:201], v[200:201], v[136:137], v[222:223] op_sel_hi:[1,0,1]
	v_pk_mul_f32 v[222:223], v[194:195], v[142:143] op_sel:[1,0] op_sel_hi:[0,0]
	v_cvt_f32_i32_e32 v134, v134
	v_pk_fma_f32 v[226:227], v[194:195], v[138:139], v[222:223] neg_lo:[0,0,1] neg_hi:[0,0,1]
	v_pk_fma_f32 v[194:195], v[194:195], v[138:139], v[222:223] op_sel_hi:[1,0,1]
	v_pk_mul_f32 v[222:223], v[34:35], v[132:133] op_sel_hi:[1,0]
	v_add_u32_e32 v133, 19, v133
	v_cvt_f32_i32_e32 v136, v133
	v_mul_f32_e32 v133, 0xbedb7629, v134
	v_exp_f32_e32 v134, v133
	v_pk_mul_f32 v[132:133], v[32:33], v[132:133] op_sel_hi:[1,0]
	v_mul_f32_e32 v136, 0xbedb7629, v136
	v_exp_f32_e32 v136, v136
	v_mul_f32_e32 v134, 0.15915494, v134
	v_mul_f32_e32 v134, v134, v131
	v_fract_f32_e32 v138, v134
	v_mul_f32_e32 v134, 0.15915494, v136
	v_mul_f32_e32 v131, v134, v131
	v_fract_f32_e32 v131, v131
	v_sin_f32_e32 v134, v138
	v_cos_f32_e32 v136, v138
	v_sin_f32_e32 v142, v131
	v_cos_f32_e32 v138, v131
	v_pk_mul_f32 v[228:229], v[132:133], v[134:135] op_sel:[1,0] op_sel_hi:[0,0]
	v_pk_fma_f32 v[230:231], v[132:133], v[136:137], v[228:229] neg_lo:[0,0,1] neg_hi:[0,0,1]
	v_pk_fma_f32 v[228:229], v[132:133], v[136:137], v[228:229] op_sel_hi:[1,0,1]
	v_pk_mul_f32 v[132:133], v[222:223], v[142:143] op_sel:[1,0] op_sel_hi:[0,0]
	v_pk_fma_f32 v[232:233], v[222:223], v[138:139], v[132:133] neg_lo:[0,0,1] neg_hi:[0,0,1]
	v_pk_fma_f32 v[222:223], v[222:223], v[138:139], v[132:133] op_sel_hi:[1,0,1]
	v_lshlrev_b64 v[132:133], 10, v[190:191]
	v_lshl_add_u64 v[190:191], v[128:129], 0, v[132:133]
	v_cvt_pk_bf16_f32 v132, v192, v137
	v_cvt_pk_bf16_f32 v133, v140, v135
	v_cvt_pk_bf16_f32 v134, v198, v143
	v_cvt_pk_bf16_f32 v135, v196, v139
	global_store_dwordx4 v[190:191], v[132:135], off nt
	v_and_b32_e32 v131, 0xfef, v188
	v_cmp_gt_i32_e32 vcc, s53, v188
	v_cvt_pk_bf16_f32 v132, v224, v201
	v_cvt_pk_bf16_f32 v133, v226, v195
	v_cvt_pk_bf16_f32 v134, v230, v229
	v_cvt_pk_bf16_f32 v135, v232, v223
	global_store_dwordx4 v[190:191], v[132:135], off offset:64 nt
	v_cndmask_b32_e32 v131, v208, v131, vcc
	v_cvt_f32_u32_e32 v131, v131
	v_mov_b32_e32 v133, v203
	v_mul_f32_e32 v132, v130, v170
	v_lshlrev_b32_e32 v133, 2, v133
	v_cvt_f32_i32_e32 v136, v133
	v_or_b32_e32 v137, 1, v133
	v_cvt_f32_i32_e32 v138, v137
	v_pk_mul_f32 v[134:135], v[30:31], v[132:133] op_sel_hi:[1,0]
	v_mul_f32_e32 v136, 0xbedb7629, v136
	v_exp_f32_e32 v139, v136
	v_mul_f32_e32 v138, 0xbedb7629, v138
	v_exp_f32_e32 v138, v138
	v_pk_mul_f32 v[136:137], v[28:29], v[132:133] op_sel_hi:[1,0]
	v_mul_f32_e32 v139, 0.15915494, v139
	v_mul_f32_e32 v139, v139, v131
	v_mul_f32_e32 v138, 0.15915494, v138
	v_fract_f32_e32 v139, v139
	v_mul_f32_e32 v138, v138, v131
	v_fract_f32_e32 v141, v138
	v_sin_f32_e32 v138, v139
	v_cos_f32_e32 v140, v139
	v_sin_f32_e32 v148, v141
	v_cos_f32_e32 v142, v141
	v_pk_mul_f32 v[138:139], v[136:137], v[138:139] op_sel:[1,0] op_sel_hi:[0,0]
	v_pk_fma_f32 v[190:191], v[136:137], v[140:141], v[138:139] neg_lo:[0,0,1] neg_hi:[0,0,1]
	v_pk_fma_f32 v[136:137], v[136:137], v[140:141], v[138:139] op_sel_hi:[1,0,1]
	v_pk_mul_f32 v[138:139], v[134:135], v[148:149] op_sel:[1,0] op_sel_hi:[0,0]
	v_pk_fma_f32 v[140:141], v[134:135], v[142:143], v[138:139] neg_lo:[0,0,1] neg_hi:[0,0,1]
	v_pk_fma_f32 v[134:135], v[134:135], v[142:143], v[138:139] op_sel_hi:[1,0,1]
	v_or_b32_e32 v136, 3, v133
	v_or_b32_e32 v134, 2, v133
	v_cvt_f32_i32_e32 v134, v134
	v_cvt_f32_i32_e32 v136, v136
	v_pk_mul_f32 v[142:143], v[24:25], v[132:133] op_sel_hi:[1,0]
	v_pk_mul_f32 v[138:139], v[26:27], v[132:133] op_sel_hi:[1,0]
	v_mul_f32_e32 v134, 0xbedb7629, v134
	v_exp_f32_e32 v134, v134
	v_mul_f32_e32 v136, 0xbedb7629, v136
	v_exp_f32_e32 v136, v136
	v_pk_mul_f32 v[198:199], v[20:21], v[132:133] op_sel_hi:[1,0]
	v_mul_f32_e32 v134, 0.15915494, v134
	v_mul_f32_e32 v134, v134, v131
	v_fract_f32_e32 v141, v134
	v_mul_f32_e32 v134, 0.15915494, v136
	v_mul_f32_e32 v134, v134, v131
	v_fract_f32_e32 v169, v134
	v_sin_f32_e32 v134, v141
	v_cos_f32_e32 v136, v141
	v_sin_f32_e32 v192, v169
	v_cos_f32_e32 v148, v169
	v_pk_mul_f32 v[194:195], v[142:143], v[134:135] op_sel:[1,0] op_sel_hi:[0,0]
	v_add_u32_e32 v134, 16, v133
	v_cvt_f32_i32_e32 v134, v134
	v_pk_fma_f32 v[196:197], v[142:143], v[136:137], v[194:195] neg_lo:[0,0,1] neg_hi:[0,0,1]
	v_pk_fma_f32 v[142:143], v[142:143], v[136:137], v[194:195] op_sel_hi:[1,0,1]
	v_add_u32_e32 v136, 17, v133
	v_cvt_f32_i32_e32 v136, v136
	v_mul_f32_e32 v134, 0xbedb7629, v134
	v_exp_f32_e32 v134, v134
	v_pk_mul_f32 v[192:193], v[138:139], v[192:193] op_sel:[1,0] op_sel_hi:[0,0]
	v_mul_f32_e32 v136, 0xbedb7629, v136
	v_exp_f32_e32 v136, v136
	v_mul_f32_e32 v134, 0.15915494, v134
	v_pk_fma_f32 v[194:195], v[138:139], v[148:149], v[192:193] neg_lo:[0,0,1] neg_hi:[0,0,1]
	v_pk_fma_f32 v[138:139], v[138:139], v[148:149], v[192:193] op_sel_hi:[1,0,1]
	v_mul_f32_e32 v134, v134, v131
	v_fract_f32_e32 v138, v134
	v_mul_f32_e32 v134, 0.15915494, v136
	v_mul_f32_e32 v134, v134, v131
	v_fract_f32_e32 v141, v134
	v_sin_f32_e32 v134, v138
	v_cos_f32_e32 v136, v138
	v_sin_f32_e32 v142, v141
	v_cos_f32_e32 v138, v141
	v_pk_mul_f32 v[192:193], v[22:23], v[132:133] op_sel_hi:[1,0]
	v_pk_mul_f32 v[200:201], v[198:199], v[134:135] op_sel:[1,0] op_sel_hi:[0,0]
	v_add_u32_e32 v134, 18, v133
	v_pk_fma_f32 v[222:223], v[198:199], v[136:137], v[200:201] neg_lo:[0,0,1] neg_hi:[0,0,1]
	v_pk_fma_f32 v[198:199], v[198:199], v[136:137], v[200:201] op_sel_hi:[1,0,1]
	v_pk_mul_f32 v[200:201], v[192:193], v[142:143] op_sel:[1,0] op_sel_hi:[0,0]
	v_cvt_f32_i32_e32 v134, v134
	v_pk_fma_f32 v[224:225], v[192:193], v[138:139], v[200:201] neg_lo:[0,0,1] neg_hi:[0,0,1]
	v_pk_fma_f32 v[192:193], v[192:193], v[138:139], v[200:201] op_sel_hi:[1,0,1]
	v_pk_mul_f32 v[200:201], v[18:19], v[132:133] op_sel_hi:[1,0]
	v_add_u32_e32 v133, 19, v133
	v_cvt_f32_i32_e32 v136, v133
	v_mul_f32_e32 v133, 0xbedb7629, v134
	v_exp_f32_e32 v134, v133
	v_pk_mul_f32 v[132:133], v[16:17], v[132:133] op_sel_hi:[1,0]
	v_mul_f32_e32 v136, 0xbedb7629, v136
	v_exp_f32_e32 v136, v136
	v_mul_f32_e32 v134, 0.15915494, v134
	v_mul_f32_e32 v134, v134, v131
	v_fract_f32_e32 v138, v134
	v_mul_f32_e32 v134, 0.15915494, v136
	v_mul_f32_e32 v131, v134, v131
	v_fract_f32_e32 v131, v131
	v_sin_f32_e32 v134, v138
	v_cos_f32_e32 v136, v138
	v_sin_f32_e32 v142, v131
	v_cos_f32_e32 v138, v131
	v_pk_mul_f32 v[226:227], v[132:133], v[134:135] op_sel:[1,0] op_sel_hi:[0,0]
	v_pk_fma_f32 v[228:229], v[132:133], v[136:137], v[226:227] neg_lo:[0,0,1] neg_hi:[0,0,1]
	v_pk_fma_f32 v[226:227], v[132:133], v[136:137], v[226:227] op_sel_hi:[1,0,1]
	v_pk_mul_f32 v[132:133], v[200:201], v[142:143] op_sel:[1,0] op_sel_hi:[0,0]
	v_pk_fma_f32 v[230:231], v[200:201], v[138:139], v[132:133] neg_lo:[0,0,1] neg_hi:[0,0,1]
	v_pk_fma_f32 v[200:201], v[200:201], v[138:139], v[132:133] op_sel_hi:[1,0,1]
	v_lshlrev_b64 v[132:133], 10, v[188:189]
	v_and_b32_e32 v131, 0xfff, v186
	v_cmp_gt_i32_e32 vcc, s53, v186
	v_lshl_add_u64 v[188:189], v[128:129], 0, v[132:133]
	v_cvt_pk_bf16_f32 v132, v190, v137
	v_cvt_pk_bf16_f32 v133, v140, v135
	v_cvt_pk_bf16_f32 v134, v196, v143
	v_cvt_pk_bf16_f32 v135, v194, v139
	v_cndmask_b32_e32 v131, v208, v131, vcc
	global_store_dwordx4 v[188:189], v[132:135], off nt
	v_cvt_f32_u32_e32 v169, v131
	v_mov_b32_e32 v131, v203
	v_cvt_pk_bf16_f32 v132, v222, v199
	v_cvt_pk_bf16_f32 v133, v224, v193
	v_cvt_pk_bf16_f32 v134, v228, v227
	v_cvt_pk_bf16_f32 v135, v230, v201
	global_store_dwordx4 v[188:189], v[132:135], off offset:64 nt
	v_mul_f32_e32 v130, v130, v168
	v_lshlrev_b32_e32 v131, 2, v131
	v_cvt_f32_i32_e32 v134, v131
	v_or_b32_e32 v135, 1, v131
	v_cvt_f32_i32_e32 v136, v135
	v_pk_mul_f32 v[132:133], v[14:15], v[130:131] op_sel_hi:[1,0]
	v_mul_f32_e32 v134, 0xbedb7629, v134
	v_exp_f32_e32 v137, v134
	v_mul_f32_e32 v136, 0xbedb7629, v136
	v_exp_f32_e32 v136, v136
	v_pk_mul_f32 v[134:135], v[12:13], v[130:131] op_sel_hi:[1,0]
	v_mul_f32_e32 v137, 0.15915494, v137
	v_mul_f32_e32 v137, v137, v169
	v_mul_f32_e32 v136, 0.15915494, v136
	v_fract_f32_e32 v137, v137
	v_mul_f32_e32 v136, v136, v169
	v_fract_f32_e32 v139, v136
	v_sin_f32_e32 v136, v137
	v_cos_f32_e32 v138, v137
	v_sin_f32_e32 v142, v139
	v_cos_f32_e32 v140, v139
	v_pk_mul_f32 v[136:137], v[134:135], v[136:137] op_sel:[1,0] op_sel_hi:[0,0]
	v_pk_fma_f32 v[188:189], v[134:135], v[138:139], v[136:137] neg_lo:[0,0,1] neg_hi:[0,0,1]
	v_pk_fma_f32 v[134:135], v[134:135], v[138:139], v[136:137] op_sel_hi:[1,0,1]
	v_pk_mul_f32 v[136:137], v[132:133], v[142:143] op_sel:[1,0] op_sel_hi:[0,0]
	v_pk_fma_f32 v[138:139], v[132:133], v[140:141], v[136:137] neg_lo:[0,0,1] neg_hi:[0,0,1]
	v_pk_fma_f32 v[132:133], v[132:133], v[140:141], v[136:137] op_sel_hi:[1,0,1]
	v_or_b32_e32 v134, 3, v131
	v_or_b32_e32 v132, 2, v131
	v_cvt_f32_i32_e32 v132, v132
	v_cvt_f32_i32_e32 v134, v134
	v_pk_mul_f32 v[140:141], v[8:9], v[130:131] op_sel_hi:[1,0]
	v_pk_mul_f32 v[136:137], v[10:11], v[130:131] op_sel_hi:[1,0]
	v_mul_f32_e32 v132, 0xbedb7629, v132
	v_exp_f32_e32 v132, v132
	v_mul_f32_e32 v134, 0xbedb7629, v134
	v_exp_f32_e32 v134, v134
	v_mul_f32_e32 v132, 0.15915494, v132
	v_mul_f32_e32 v132, v132, v169
	v_fract_f32_e32 v139, v132
	v_mul_f32_e32 v132, 0.15915494, v134
	v_mul_f32_e32 v132, v132, v169
	v_fract_f32_e32 v143, v132
	v_sin_f32_e32 v132, v139
	v_cos_f32_e32 v134, v139
	v_sin_f32_e32 v148, v143
	v_cos_f32_e32 v142, v143
	v_pk_mul_f32 v[190:191], v[140:141], v[132:133] op_sel:[1,0] op_sel_hi:[0,0]
	v_add_u32_e32 v132, 16, v131
	v_cvt_f32_i32_e32 v132, v132
	v_pk_fma_f32 v[192:193], v[140:141], v[134:135], v[190:191] neg_lo:[0,0,1] neg_hi:[0,0,1]
	v_pk_fma_f32 v[140:141], v[140:141], v[134:135], v[190:191] op_sel_hi:[1,0,1]
	v_add_u32_e32 v134, 17, v131
	v_cvt_f32_i32_e32 v134, v134
	v_mul_f32_e32 v132, 0xbedb7629, v132
	v_exp_f32_e32 v132, v132
	v_pk_mul_f32 v[190:191], v[136:137], v[148:149] op_sel:[1,0] op_sel_hi:[0,0]
	v_mul_f32_e32 v134, 0xbedb7629, v134
	v_exp_f32_e32 v134, v134
	v_mul_f32_e32 v132, 0.15915494, v132
	v_pk_fma_f32 v[194:195], v[136:137], v[142:143], v[190:191] neg_lo:[0,0,1] neg_hi:[0,0,1]
	v_pk_fma_f32 v[136:137], v[136:137], v[142:143], v[190:191] op_sel_hi:[1,0,1]
	v_mul_f32_e32 v132, v132, v169
	v_fract_f32_e32 v136, v132
	v_mul_f32_e32 v132, 0.15915494, v134
	v_mul_f32_e32 v132, v132, v169
	v_fract_f32_e32 v139, v132
	v_sin_f32_e32 v132, v136
	v_cos_f32_e32 v134, v136
	v_sin_f32_e32 v140, v139
	v_cos_f32_e32 v136, v139
	v_pk_mul_f32 v[190:191], v[4:5], v[130:131] op_sel_hi:[1,0]
	v_pk_mul_f32 v[142:143], v[6:7], v[130:131] op_sel_hi:[1,0]
	v_pk_mul_f32 v[196:197], v[190:191], v[132:133] op_sel:[1,0] op_sel_hi:[0,0]
	v_add_u32_e32 v132, 18, v131
	v_pk_fma_f32 v[198:199], v[190:191], v[134:135], v[196:197] neg_lo:[0,0,1] neg_hi:[0,0,1]
	v_pk_fma_f32 v[190:191], v[190:191], v[134:135], v[196:197] op_sel_hi:[1,0,1]
	v_pk_mul_f32 v[196:197], v[142:143], v[140:141] op_sel:[1,0] op_sel_hi:[0,0]
	v_cvt_f32_i32_e32 v132, v132
	v_pk_fma_f32 v[200:201], v[142:143], v[136:137], v[196:197] neg_lo:[0,0,1] neg_hi:[0,0,1]
	v_pk_fma_f32 v[142:143], v[142:143], v[136:137], v[196:197] op_sel_hi:[1,0,1]
	v_pk_mul_f32 v[196:197], v[2:3], v[130:131] op_sel_hi:[1,0]
	v_add_u32_e32 v131, 19, v131
	v_cvt_f32_i32_e32 v134, v131
	v_mul_f32_e32 v131, 0xbedb7629, v132
	v_exp_f32_e32 v132, v131
	v_pk_mul_f32 v[130:131], v[0:1], v[130:131] op_sel_hi:[1,0]
	v_mul_f32_e32 v134, 0xbedb7629, v134
	v_exp_f32_e32 v134, v134
	v_mul_f32_e32 v132, 0.15915494, v132
	v_mul_f32_e32 v132, v132, v169
	v_fract_f32_e32 v136, v132
	v_mul_f32_e32 v132, 0.15915494, v134
	v_mul_f32_e32 v132, v132, v169
	v_fract_f32_e32 v139, v132
	v_sin_f32_e32 v132, v136
	v_cos_f32_e32 v134, v136
	v_sin_f32_e32 v140, v139
	v_cos_f32_e32 v136, v139
	v_pk_mul_f32 v[222:223], v[130:131], v[132:133] op_sel:[1,0] op_sel_hi:[0,0]
	v_pk_fma_f32 v[224:225], v[130:131], v[134:135], v[222:223] neg_lo:[0,0,1] neg_hi:[0,0,1]
	v_pk_fma_f32 v[222:223], v[130:131], v[134:135], v[222:223] op_sel_hi:[1,0,1]
	v_pk_mul_f32 v[130:131], v[196:197], v[140:141] op_sel:[1,0] op_sel_hi:[0,0]
	v_pk_fma_f32 v[226:227], v[196:197], v[136:137], v[130:131] neg_lo:[0,0,1] neg_hi:[0,0,1]
	v_pk_fma_f32 v[196:197], v[196:197], v[136:137], v[130:131] op_sel_hi:[1,0,1]
	v_lshlrev_b64 v[130:131], 10, v[186:187]
	v_lshl_add_u64 v[186:187], v[128:129], 0, v[130:131]
	v_cvt_pk_bf16_f32 v128, v188, v135
	v_cvt_pk_bf16_f32 v129, v138, v133
	v_cvt_pk_bf16_f32 v130, v192, v141
	v_cvt_pk_bf16_f32 v131, v194, v137
	global_store_dwordx4 v[186:187], v[128:131], off nt
	s_nop 1
	v_cvt_pk_bf16_f32 v128, v198, v191
	v_cvt_pk_bf16_f32 v129, v200, v143
	v_cvt_pk_bf16_f32 v130, v224, v223
	v_cvt_pk_bf16_f32 v131, v226, v197
	global_store_dwordx4 v[186:187], v[128:131], off offset:64 nt

.LBB0_366:
	s_andn2_b64 vcc, exec, s[36:37]
	s_cbranch_vccnz .LBB0_404
	v_pk_mul_f32 v[130:131], v[126:127], v[184:185] op_sel_hi:[1,0]
	v_pk_mul_f32 v[128:129], v[124:125], v[184:185] op_sel_hi:[1,0]
	v_pk_mul_f32 v[134:135], v[122:123], v[184:185] op_sel_hi:[1,0]
	v_pk_mul_f32 v[132:133], v[120:121], v[184:185] op_sel_hi:[1,0]
	v_lshlrev_b64 v[186:187], 8, v[176:177]
	v_pk_mul_f32 v[138:139], v[118:119], v[184:185] op_sel_hi:[1,0]
	v_pk_mul_f32 v[136:137], v[116:117], v[184:185] op_sel_hi:[1,0]
	v_pk_mul_f32 v[142:143], v[114:115], v[184:185] op_sel_hi:[1,0]
	v_pk_mul_f32 v[140:141], v[112:113], v[184:185] op_sel_hi:[1,0]
	v_lshl_add_u64 v[190:191], v[152:153], 0, v[186:187]
	v_cvt_pk_bf16_f32 v186, v128, v129
	v_cvt_pk_bf16_f32 v187, v130, v131
	v_cvt_pk_bf16_f32 v188, v132, v133
	v_cvt_pk_bf16_f32 v189, v134, v135
	global_store_dwordx4 v[190:191], v[186:189], off nt
	v_lshl_or_b32 v148, v176, 4, v218
	s_cmpk_lt_i32 s67, 0x80
	v_cvt_pk_bf16_f32 v186, v136, v137
	v_cvt_pk_bf16_f32 v187, v138, v139
	v_cvt_pk_bf16_f32 v188, v140, v141
	v_cvt_pk_bf16_f32 v189, v142, v143
	global_store_dwordx4 v[190:191], v[186:189], off offset:64 nt
	s_cselect_b64 s[36:37], -1, 0
	s_cmpk_gt_i32 s67, 0x7f
	v_add_u32_e32 v186, v148, v209
	v_ashrrev_i32_e32 v187, 31, v186
	v_lshlrev_b64 v[186:187], 9, v[186:187]
	v_lshl_add_u64 v[186:187], v[154:155], 0, v[186:187]
	s_cselect_b64 s[6:7], -1, 0
	v_cmp_ne_u64_e32 vcc, 0, v[186:187]
	s_and_b64 s[68:69], s[6:7], vcc
	s_and_saveexec_b64 s[38:39], s[68:69]
	s_cbranch_execz .LBB0_369
	v_lshlrev_b32_e32 v148, 2, v150
	v_lshl_add_u64 v[186:187], v[186:187], 0, v[148:149]
	global_store_dwordx4 v[186:187], v[128:131], off
	global_store_dwordx4 v[186:187], v[132:135], off offset:16
	global_store_dwordx4 v[186:187], v[136:139], off offset:128
	global_store_dwordx4 v[186:187], v[140:143], off offset:144

.LBB0_407:
	v_pk_mul_f32 v[132:133], v[124:125], v[184:185] op_sel_hi:[1,0]
	v_pk_mul_f32 v[136:137], v[116:117], v[184:185] op_sel_hi:[1,0]
	v_pk_mul_f32 v[130:131], v[126:127], v[184:185] op_sel_hi:[1,0]
	v_pk_mul_f32 v[126:127], v[120:121], v[184:185] op_sel_hi:[1,0]
	v_pk_mul_f32 v[134:135], v[118:119], v[184:185] op_sel_hi:[1,0]
	v_pk_mul_f32 v[120:121], v[114:115], v[184:185] op_sel_hi:[1,0]
	v_mov_b32_e32 v114, v133
	v_mov_b32_e32 v115, v137
	v_pk_mul_f32 v[124:125], v[122:123], v[184:185] op_sel_hi:[1,0]
	v_pk_mul_f32 v[122:123], v[112:113], v[184:185] op_sel_hi:[1,0]
	v_mov_b32_e32 v112, v132
	v_mov_b32_e32 v113, v136
	v_pk_mul_f32 v[114:115], v[114:115], v[114:115]
	v_mov_b32_e32 v116, v131
	v_mov_b32_e32 v117, v135
	v_pk_fma_f32 v[112:113], v[112:113], v[112:113], v[114:115]
	v_mov_b32_e32 v114, v130
	v_mov_b32_e32 v115, v134
	v_pk_mul_f32 v[116:117], v[116:117], v[116:117]
	v_mov_b32_e32 v118, v125
	v_pk_fma_f32 v[114:115], v[114:115], v[114:115], v[116:117]
	v_mov_b32_e32 v116, v127
	v_mov_b32_e32 v117, v123
	v_pk_add_f32 v[112:113], v[112:113], v[114:115]
	v_mov_b32_e32 v114, v126
	v_mov_b32_e32 v115, v122
	v_pk_mul_f32 v[116:117], v[116:117], v[116:117]
	v_mov_b32_e32 v119, v121
	v_and_b32_e32 v129, 64, v219
	v_pk_fma_f32 v[114:115], v[114:115], v[114:115], v[116:117]
	v_mov_b32_e32 v116, v124
	v_mov_b32_e32 v117, v120
	v_pk_mul_f32 v[118:119], v[118:119], v[118:119]
	v_xor_b32_e32 v128, 16, v219
	v_add_u32_e32 v129, 64, v129
	v_pk_fma_f32 v[116:117], v[116:117], v[116:117], v[118:119]
	v_cmp_lt_i32_e32 vcc, v128, v129
	v_pk_add_f32 v[114:115], v[114:115], v[116:117]
	v_lshlrev_b32_e32 v148, 2, v150
	v_cndmask_b32_e32 v128, v219, v128, vcc
	v_pk_add_f32 v[112:113], v[112:113], v[114:115]
	v_lshlrev_b32_e32 v139, 2, v128
	v_add_f32_e32 v112, v112, v113
	ds_bpermute_b32 v113, v139, v112
	v_xor_b32_e32 v128, 32, v219
	v_cmp_lt_i32_e32 vcc, v128, v129
	s_mov_b64 s[38:39], -1
	s_waitcnt lgkmcnt(0)
	v_add_f32_e32 v112, v112, v113
	v_cndmask_b32_e32 v128, v219, v128, vcc
	v_lshlrev_b32_e32 v138, 2, v128
	ds_bpermute_b32 v113, v138, v112
	v_cmp_gt_i32_e32 vcc, s53, v176
	s_waitcnt lgkmcnt(0)
	v_add_f32_e32 v112, v112, v113
	v_fmamk_f32 v112, v112, 0x3c800000, v216
	v_rsq_f32_e32 v128, v112
	global_load_dwordx4 v[112:115], v148, s[36:37] offset:16
	global_load_dwordx4 v[116:119], v148, s[36:37]
	v_pk_mul_f32 v[132:133], v[132:133], v[128:129] op_sel_hi:[1,0]
	v_pk_mul_f32 v[130:131], v[130:131], v[128:129] op_sel_hi:[1,0]
	v_pk_mul_f32 v[140:141], v[134:135], v[128:129] op_sel_hi:[1,0]
	v_pk_mul_f32 v[142:143], v[136:137], v[128:129] op_sel_hi:[1,0]
	v_and_b32_e32 v129, 0xfcf, v176
	v_cndmask_b32_e32 v129, v208, v129, vcc
	v_cvt_f32_u32_e32 v129, v129
	s_and_b64 vcc, exec, s[2:3]
	s_waitcnt vmcnt(0)
	v_pk_mul_f32 v[130:131], v[118:119], v[130:131]
	v_pk_mul_f32 v[132:133], v[116:117], v[132:133]
	global_load_dwordx4 v[116:119], v148, s[36:37] offset:144
	global_load_dwordx4 v[134:137], v148, s[36:37] offset:128
	s_waitcnt vmcnt(0)
	v_pk_mul_f32 v[136:137], v[136:137], v[140:141]
	v_mov_b32_e32 v140, v203
	v_pk_mul_f32 v[134:135], v[134:135], v[142:143]
	v_lshlrev_b32_e32 v169, 3, v140
	v_cvt_f32_i32_e32 v140, v169
	v_or_b32_e32 v173, 6, v169
	v_cvt_f32_i32_e32 v173, v173
	v_mul_f32_e32 v140, 0xbed49a78, v140
	v_exp_f32_e32 v140, v140
	v_mul_f32_e32 v173, 0xbed49a78, v173
	v_exp_f32_e32 v173, v173
	v_mul_f32_e32 v140, 0.15915494, v140
	v_mul_f32_e32 v140, v140, v129
	v_fract_f32_e32 v141, v140
	v_or_b32_e32 v140, 4, v169
	v_cvt_f32_i32_e32 v140, v140
	v_sin_f32_e32 v142, v141
	v_mul_f32_e32 v173, 0.15915494, v173
	v_mul_f32_e32 v173, v173, v129
	v_mul_f32_e32 v140, 0xbed49a78, v140
	v_exp_f32_e32 v140, v140
	v_fract_f32_e32 v173, v173
	v_cos_f32_e32 v192, v173
	v_sin_f32_e32 v194, v173
	v_mul_f32_e32 v140, 0.15915494, v140
	v_mul_f32_e32 v140, v140, v129
	v_fract_f32_e32 v143, v140
	v_cos_f32_e32 v140, v141
	v_or_b32_e32 v141, 1, v169
	v_cvt_f32_i32_e32 v141, v141
	v_cos_f32_e32 v184, v143
	v_sin_f32_e32 v186, v143
	v_mul_f32_e32 v141, 0xbed49a78, v141
	v_exp_f32_e32 v141, v141
	s_nop 0
	v_mul_f32_e32 v141, 0.15915494, v141
	v_mul_f32_e32 v141, v141, v129
	v_fract_f32_e32 v143, v141
	v_or_b32_e32 v141, 5, v169
	v_cvt_f32_i32_e32 v141, v141
	v_mul_f32_e32 v141, 0xbed49a78, v141
	v_exp_f32_e32 v141, v141
	s_nop 0
	v_mul_f32_e32 v141, 0.15915494, v141
	v_mul_f32_e32 v141, v141, v129
	v_fract_f32_e32 v171, v141
	v_cos_f32_e32 v185, v171
	v_sin_f32_e32 v187, v171
	v_or_b32_e32 v171, 2, v169
	v_cvt_f32_i32_e32 v171, v171
	v_cos_f32_e32 v141, v143
	v_sin_f32_e32 v143, v143
	v_mul_f32_e32 v171, 0xbed49a78, v171
	v_exp_f32_e32 v171, v171
	s_nop 0
	v_mul_f32_e32 v171, 0.15915494, v171
	v_mul_f32_e32 v171, v171, v129
	v_fract_f32_e32 v171, v171
	v_cos_f32_e32 v188, v171
	v_sin_f32_e32 v190, v171
	v_or_b32_e32 v171, 3, v169
	v_cvt_f32_i32_e32 v171, v171
	v_or_b32_e32 v169, 7, v169
	v_cvt_f32_i32_e32 v169, v169
	v_mul_f32_e32 v171, 0xbed49a78, v171
	v_exp_f32_e32 v171, v171
	v_mul_f32_e32 v169, 0xbed49a78, v169
	v_exp_f32_e32 v169, v169
	v_mul_f32_e32 v171, 0.15915494, v171
	v_mul_f32_e32 v171, v171, v129
	v_fract_f32_e32 v171, v171
	v_mul_f32_e32 v169, 0.15915494, v169
	v_mul_f32_e32 v129, v169, v129
	v_sin_f32_e32 v191, v171
	v_fract_f32_e32 v129, v129
	v_cos_f32_e32 v189, v171
	v_pk_mul_f32 v[126:127], v[126:127], v[128:129] op_sel_hi:[1,0]
	v_pk_mul_f32 v[124:125], v[124:125], v[128:129] op_sel_hi:[1,0]
	v_pk_mul_f32 v[126:127], v[112:113], v[126:127]
	v_pk_mul_f32 v[124:125], v[114:115], v[124:125]
	v_pk_mul_f32 v[112:113], v[120:121], v[128:129] op_sel_hi:[1,0]
	v_pk_mul_f32 v[114:115], v[122:123], v[128:129] op_sel_hi:[1,0]
	v_cos_f32_e32 v193, v129
	v_sin_f32_e32 v195, v129
	v_pk_mul_f32 v[116:117], v[116:117], v[114:115]
	v_pk_mul_f32 v[118:119], v[118:119], v[112:113]
	v_pk_mul_f32 v[112:113], v[136:137], v[190:191]
	v_pk_mul_f32 v[114:115], v[134:135], v[142:143]
	v_pk_fma_f32 v[112:113], v[130:131], v[188:189], v[112:113] neg_lo:[0,0,1] neg_hi:[0,0,1]
	v_pk_fma_f32 v[120:121], v[132:133], v[140:141], v[114:115] neg_lo:[0,0,1] neg_hi:[0,0,1]
	v_pk_mul_f32 v[114:115], s[6:7], v[112:113] op_sel_hi:[0,1]
	v_pk_mul_f32 v[112:113], s[6:7], v[120:121] op_sel_hi:[0,1]
	v_pk_mul_f32 v[120:121], v[136:137], v[188:189]
	v_pk_mul_f32 v[122:123], v[134:135], v[140:141]
	v_pk_fma_f32 v[120:121], v[130:131], v[190:191], v[120:121]
	v_pk_fma_f32 v[128:129], v[132:133], v[142:143], v[122:123]
	v_pk_mul_f32 v[122:123], s[6:7], v[120:121] op_sel_hi:[0,1]
	v_pk_mul_f32 v[120:121], s[6:7], v[128:129] op_sel_hi:[0,1]
	v_pk_mul_f32 v[128:129], v[118:119], v[194:195]
	v_pk_mul_f32 v[130:131], v[116:117], v[186:187]
	v_pk_mul_f32 v[118:119], v[118:119], v[192:193]
	v_pk_mul_f32 v[116:117], v[116:117], v[184:185]
	v_pk_fma_f32 v[132:133], v[126:127], v[184:185], v[130:131] neg_lo:[0,0,1] neg_hi:[0,0,1]
	v_pk_fma_f32 v[128:129], v[124:125], v[192:193], v[128:129] neg_lo:[0,0,1] neg_hi:[0,0,1]
	v_pk_fma_f32 v[116:117], v[126:127], v[186:187], v[116:117]
	v_pk_fma_f32 v[118:119], v[124:125], v[194:195], v[118:119]
	v_pk_mul_f32 v[130:131], s[6:7], v[128:129] op_sel_hi:[0,1]
	v_pk_mul_f32 v[128:129], s[6:7], v[132:133] op_sel_hi:[0,1]
	v_pk_mul_f32 v[134:135], s[6:7], v[118:119] op_sel_hi:[0,1]
	v_pk_mul_f32 v[132:133], s[6:7], v[116:117] op_sel_hi:[0,1]
	v_cvt_pk_bf16_f32 v116, v112, v113
	v_cvt_pk_bf16_f32 v117, v114, v115
	v_cvt_pk_bf16_f32 v118, v128, v129
	v_cvt_pk_bf16_f32 v119, v130, v131
	v_cvt_pk_bf16_f32 v124, v120, v121
	v_cvt_pk_bf16_f32 v125, v122, v123
	v_cvt_pk_bf16_f32 v126, v132, v133
	v_cvt_pk_bf16_f32 v127, v134, v135
	s_cbranch_vccz .LBB0_411
	v_lshlrev_b64 v[136:137], 8, v[176:177]
	v_lshl_add_u64 v[136:137], v[158:159], 0, v[136:137]
	global_store_dwordx4 v[136:137], v[116:119], off nt
	global_store_dwordx4 v[136:137], v[124:127], off offset:64 nt
	v_lshl_or_b32 v136, v176, 4, v218
	v_add_u32_e32 v136, v136, v209
	v_ashrrev_i32_e32 v137, 31, v136
	v_lshlrev_b64 v[136:137], 9, v[136:137]
	s_cmpk_gt_i32 s67, 0x7f
	v_lshl_add_u64 v[136:137], s[28:29], 0, v[136:137]
	s_cselect_b64 s[2:3], -1, 0
	v_cmp_ne_u64_e32 vcc, 0, v[136:137]
	s_and_b64 s[38:39], s[2:3], vcc
	s_and_saveexec_b64 s[2:3], s[38:39]
	s_cbranch_execz .LBB0_410
	v_lshl_add_u64 v[136:137], v[136:137], 0, v[148:149]
	global_store_dwordx4 v[136:137], v[112:115], off
	global_store_dwordx4 v[136:137], v[128:131], off offset:16
	global_store_dwordx4 v[136:137], v[120:123], off offset:128
	global_store_dwordx4 v[136:137], v[132:135], off offset:144
